# attention epilogues: 2-byte global stores replaced by LDS transpose in the wave's Q region + 16-byte global stores
# baseline (speedup 1.0000x reference)
; #define SBAR() __builtin_amdgcn_sched_barrier(0)
; template <bool DIFF> ...
;     ...
;       { const float x1 = fmaf(cb1, C, e1), x2 = fmaf(cb1, C, e2);
; #pragma unroll
;       for (int r = 0; r < 16; ++r) a1[r] = __builtin_amdgcn_exp2f(fmaf(a1[r], C, x1));
;       if (DIFF) {
; #pragma unroll
;         for (int r = 0; r < 16; ++r) a1[r] = fmaf(nsg, __builtin_amdgcn_exp2f(fmaf(b1[r], C, x2)), a1[r]);
;       } }
;       PK4(a1, 0, pa2); PK4(a1, 8, pa3);
;       SBAR();
;       pv_step<2>(o, vb0, pa2); pv_step<3>(o, vb0, pa3);
;       }
;     ...
;     }
;   }
;   bf16* Ow = Ob + (size_t)(wid * 32) * 2048;
;   if (DIFF) {
;     float gsub[4];
; #pragma unroll
;     for (int d = 0; d < 4; ++d) gsub[d] = subg[32 * d + r32] * 0.8f;
; #pragma unroll
;     for (int r = 0; r < 16; ++r) {
;       float ss = o[0][r] * o[0][r] + o[1][r] * o[1][r] + o[2][r] * o[2][r] + o[3][r] * o[3][r];
;       ss += __shfl_xor(ss, 1); ss += __shfl_xor(ss, 2); ss += __shfl_xor(ss, 4); ss += __shfl_xor(ss, 8); ss += __shfl_xor(ss, 16);
;       const float rs = 1.0f / sqrtf(ss * (1.0f / 128.0f) + 1e-6f);
.LBB0_260:
	s_or_b64 exec, exec, s[4:5]
	s_waitcnt lgkmcnt(0)
	v_fmac_f32_e32 v188, 0x3e38aa3b, v96
	v_fmac_f32_e32 v187, 0x3e38aa3b, v96
	v_fmamk_f32 v80, v80, 0x3e38aa3b, v188
	v_fmamk_f32 v81, v81, 0x3e38aa3b, v188
	v_fmamk_f32 v82, v82, 0x3e38aa3b, v188
	v_fmamk_f32 v83, v83, 0x3e38aa3b, v188
	v_fmamk_f32 v84, v84, 0x3e38aa3b, v188
	v_fmamk_f32 v85, v85, 0x3e38aa3b, v188
	v_fmamk_f32 v86, v86, 0x3e38aa3b, v188
	v_fmamk_f32 v87, v87, 0x3e38aa3b, v188
	v_fmamk_f32 v88, v88, 0x3e38aa3b, v188
	v_fmamk_f32 v89, v89, 0x3e38aa3b, v188
	v_fmamk_f32 v90, v90, 0x3e38aa3b, v188
	v_fmamk_f32 v91, v91, 0x3e38aa3b, v188
	v_fmamk_f32 v92, v92, 0x3e38aa3b, v188
	v_fmamk_f32 v93, v93, 0x3e38aa3b, v188
	v_fmamk_f32 v94, v94, 0x3e38aa3b, v188
	v_fmac_f32_e32 v188, 0x3e38aa3b, v95
	v_fmamk_f32 v64, v64, 0x3e38aa3b, v187
	v_fmamk_f32 v65, v65, 0x3e38aa3b, v187
	v_fmamk_f32 v66, v66, 0x3e38aa3b, v187
	v_fmamk_f32 v67, v67, 0x3e38aa3b, v187
	v_fmamk_f32 v68, v68, 0x3e38aa3b, v187
	v_fmamk_f32 v69, v69, 0x3e38aa3b, v187
	v_fmamk_f32 v70, v70, 0x3e38aa3b, v187
	v_fmamk_f32 v71, v71, 0x3e38aa3b, v187
	v_fmamk_f32 v72, v72, 0x3e38aa3b, v187
	v_fmamk_f32 v73, v73, 0x3e38aa3b, v187
	v_fmamk_f32 v74, v74, 0x3e38aa3b, v187
	v_fmamk_f32 v75, v75, 0x3e38aa3b, v187
	v_fmamk_f32 v76, v76, 0x3e38aa3b, v187
	v_fmamk_f32 v77, v77, 0x3e38aa3b, v187
	v_fmamk_f32 v78, v78, 0x3e38aa3b, v187
	v_fmac_f32_e32 v187, 0x3e38aa3b, v79
	v_exp_f32_e32 v80, v80
	v_exp_f32_e32 v81, v81
	v_exp_f32_e32 v82, v82
	v_exp_f32_e32 v83, v83
	v_exp_f32_e32 v84, v84
	v_exp_f32_e32 v85, v85
	v_exp_f32_e32 v86, v86
	v_exp_f32_e32 v87, v87
	v_exp_f32_e32 v88, v88
	v_exp_f32_e32 v89, v89
	v_exp_f32_e32 v90, v90
	v_exp_f32_e32 v91, v91
	v_exp_f32_e32 v92, v92
	v_exp_f32_e32 v93, v93
	v_exp_f32_e32 v94, v94
	v_exp_f32_e32 v95, v188
	v_exp_f32_e32 v64, v64
	v_exp_f32_e32 v65, v65
	v_exp_f32_e32 v66, v66
	v_exp_f32_e32 v67, v67
	v_exp_f32_e32 v68, v68
	v_exp_f32_e32 v69, v69
	v_exp_f32_e32 v70, v70
	v_exp_f32_e32 v71, v71
	v_exp_f32_e32 v72, v72
	v_exp_f32_e32 v73, v73
	v_exp_f32_e32 v74, v74
	v_exp_f32_e32 v75, v75
	v_exp_f32_e32 v76, v76
	v_exp_f32_e32 v77, v77
	v_exp_f32_e32 v78, v78
	v_exp_f32_e32 v79, v187
	s_lshl_b64 s[4:5], s[30:31], 12
	s_add_u32 s2, s42, s4
	s_addc_u32 s5, s43, s5
	v_pk_fma_f32 v[64:65], v[144:145], v[64:65], v[80:81]
	v_pk_fma_f32 v[66:67], v[144:145], v[66:67], v[82:83]
	v_pk_fma_f32 v[68:69], v[144:145], v[68:69], v[84:85]
	v_pk_fma_f32 v[70:71], v[144:145], v[70:71], v[86:87]
	v_pk_fma_f32 v[72:73], v[144:145], v[72:73], v[88:89]
	v_pk_fma_f32 v[74:75], v[144:145], v[74:75], v[90:91]
	v_pk_fma_f32 v[76:77], v[144:145], v[76:77], v[92:93]
	v_pk_fma_f32 v[78:79], v[144:145], v[78:79], v[94:95]
	s_add_u32 s4, s2, s38
	v_cvt_pk_bf16_f32 v64, v64, v65
	v_cvt_pk_bf16_f32 v65, v66, v67
	v_cvt_pk_bf16_f32 v66, v68, v69
	v_cvt_pk_bf16_f32 v67, v70, v71
	v_cvt_pk_bf16_f32 v68, v72, v73
	v_cvt_pk_bf16_f32 v69, v74, v75
	v_cvt_pk_bf16_f32 v70, v76, v77
	v_cvt_pk_bf16_f32 v71, v78, v79
	s_addc_u32 s5, s5, 0
	v_permlane32_swap_b32_e32 v64, v66
	v_permlane32_swap_b32_e32 v65, v67
	v_permlane32_swap_b32_e32 v68, v70
	v_permlane32_swap_b32_e32 v69, v71
	ds_read_b64_tr_b16 v[72:73], v146 offset:0x2000
	ds_read_b64_tr_b16 v[74:75], v146 offset:0x2800
	ds_read_b64_tr_b16 v[76:77], v146 offset:0x2200
	ds_read_b64_tr_b16 v[78:79], v146 offset:0x2a00
	ds_read_b64_tr_b16 v[80:81], v146 offset:0x2400
	ds_read_b64_tr_b16 v[82:83], v146 offset:0x2c00
	ds_read_b64_tr_b16 v[84:85], v146 offset:0x2600
	ds_read_b64_tr_b16 v[86:87], v146 offset:0x2e00
	s_waitcnt lgkmcnt(0)
	s_nop 0
	v_mfma_f32_32x32x16_bf16 v[0:15], v[64:67], v[72:75], v[0:15]
	ds_read_b64_tr_b16 v[72:73], v146 offset:0x3000
	ds_read_b64_tr_b16 v[74:75], v146 offset:0x3800
	v_mfma_f32_32x32x16_bf16 v[16:31], v[64:67], v[76:79], v[16:31]
	ds_read_b64_tr_b16 v[76:77], v146 offset:0x3200
	ds_read_b64_tr_b16 v[78:79], v146 offset:0x3a00
	v_mfma_f32_32x32x16_bf16 v[32:47], v[64:67], v[80:83], v[32:47]
	ds_read_b64_tr_b16 v[80:81], v146 offset:0x3400
	ds_read_b64_tr_b16 v[82:83], v146 offset:0x3c00
	ds_read_b64_tr_b16 v[88:89], v146 offset:0x3600
	ds_read_b64_tr_b16 v[90:91], v146 offset:0x3e00
	s_waitcnt lgkmcnt(0)
	v_mfma_f32_32x32x16_bf16 v[48:63], v[64:67], v[84:87], v[48:63]
	v_lshlrev_b32_e32 v64, 2, v164
	v_mfma_f32_32x32x16_bf16 v[0:15], v[68:71], v[72:75], v[0:15]
	global_load_dword v72, v64, s[28:29]
	global_load_dword v73, v64, s[28:29] offset:128
	global_load_dword v74, v64, s[28:29] offset:256
	global_load_dword v75, v64, s[28:29] offset:384
	v_ashrrev_i32_e32 v149, 31, v148
	v_lshlrev_b32_e32 v146, 1, v164
	v_mfma_f32_32x32x16_bf16 v[16:31], v[68:71], v[76:79], v[16:31]
	v_mfma_f32_32x32x16_bf16 v[32:47], v[68:71], v[80:83], v[32:47]
	s_nop 10
	v_mul_f32_e32 v64, v16, v16
	v_fmac_f32_e32 v64, v0, v0
	v_mfma_f32_32x32x16_bf16 v[48:63], v[68:71], v[88:91], v[48:63]
	v_fmac_f32_e32 v64, v32, v32
	s_nop 10
	v_fmac_f32_e32 v64, v48, v48
	ds_bpermute_b32 v65, v154, v64
	s_waitcnt lgkmcnt(0)
	v_add_f32_e32 v64, v64, v65
	ds_bpermute_b32 v65, v155, v64
	s_waitcnt lgkmcnt(0)
	v_add_f32_e32 v64, v64, v65
	ds_bpermute_b32 v65, v156, v64
	s_waitcnt lgkmcnt(0)
	v_add_f32_e32 v64, v64, v65
	ds_bpermute_b32 v65, v157, v64
	s_waitcnt lgkmcnt(0)
	v_add_f32_e32 v66, v64, v65
	ds_bpermute_b32 v67, v158, v66
	v_lshlrev_b32_e32 v64, 14, v165
	v_mov_b32_e32 v65, v147
	s_waitcnt lgkmcnt(0)
; #define SBAR() __builtin_amdgcn_sched_barrier(0)
; __device__ __forceinline__ int crow(int r, int hi) { return (r & 3) + 8 * (r >> 2) + 4 * hi; }
; __device__ __forceinline__ unsigned short f2bf(float f) { unsigned u = __float_as_uint(f); return (unsigned short)((u + 0x7fffu + ((u >> 16) & 1u)) >> 16); }
; __device__ __forceinline__ unsigned f2bf(float f) { unsigned u = __float_as_uint(f); return (u + 0x7fffu + ((u >> 16) & 1u)) >> 16; }
; template <bool DIFF> ...
;     ...
;     for (int r = 0; r < 16; ++r) {
;       float ss = o[0][r] * o[0][r] + o[1][r] * o[1][r] + o[2][r] * o[2][r] + o[3][r] * o[3][r];
;       ss += __shfl_xor(ss, 1); ss += __shfl_xor(ss, 2); ss += __shfl_xor(ss, 4); ss += __shfl_xor(ss, 8); ss += __shfl_xor(ss, 16);
;       const float rs = 1.0f / sqrtf(ss * (1.0f / 128.0f) + 1e-6f);
;       bf16* orow = Ow + (size_t)crow(r, hi) * 2048 + r32;
; #pragma unroll
;       for (int d = 0; d < 4; ++d) orow[32 * d] = f2bf(o[d][r] * rs * gsub[d]);
;       asm volatile("" ::: "memory"); SBAR();
	v_add_f32_e32 v66, v66, v67
	v_fmamk_f32 v66, v66, 0x3c000000, v160
	v_mul_f32_e32 v67, 0x4f800000, v66
	v_cmp_gt_f32_e32 vcc, s74, v66
	s_nop 1
	v_cndmask_b32_e32 v68, v66, v67, vcc
	v_sqrt_f32_e32 v69, v68
	v_lshlrev_b64 v[66:67], 12, v[148:149]
	v_lshl_add_u64 v[66:67], s[4:5], 0, v[66:67]
	v_lshl_add_u64 v[66:67], v[66:67], 0, v[146:147]
	v_add_u32_e32 v70, -1, v69
	v_add_u32_e32 v71, 1, v69
	v_fma_f32 v76, -v70, v69, v68
	v_fma_f32 v77, -v71, v69, v68
	v_cmp_ge_f32_e64 s[4:5], 0, v76
	v_lshl_add_u64 v[64:65], v[66:67], 0, v[64:65]
	s_nop 0
	v_cndmask_b32_e64 v69, v69, v70, s[4:5]
	v_cmp_lt_f32_e64 s[4:5], 0, v77
	s_nop 1
	v_cndmask_b32_e64 v69, v69, v71, s[4:5]
	v_mul_f32_e32 v70, 0x37800000, v69
	v_cndmask_b32_e32 v69, v69, v70, vcc
	v_cmp_class_f32_e32 vcc, v68, v161
	s_nop 1
	v_cndmask_b32_e32 v68, v69, v68, vcc
	v_div_scale_f32 v69, s[4:5], v68, v68, 1.0
	v_rcp_f32_e32 v70, v69
	v_div_scale_f32 v66, vcc, 1.0, v68, 1.0
	v_fma_f32 v67, -v69, v70, 1.0
	v_fmac_f32_e32 v70, v67, v70
	v_mul_f32_e32 v67, v66, v70
	v_fma_f32 v71, -v69, v67, v66
	v_fmac_f32_e32 v67, v71, v70
	v_fma_f32 v66, -v69, v67, v66
	v_div_fmas_f32 v66, v66, v70, v67
	v_div_fixup_f32 v66, v66, v68, 1.0
	v_mul_f32_e32 v67, v0, v66
	s_waitcnt vmcnt(3)
	v_mul_f32_e32 v0, 0x3f4ccccd, v72
	v_mul_f32_e32 v68, v16, v66
	v_mul_f32_e32 v69, v32, v66
	v_mul_f32_e32 v66, v48, v66
	s_waitcnt vmcnt(2)
	v_mul_f32_e32 v16, 0x3f4ccccd, v73
	s_waitcnt vmcnt(1)
	v_mul_f32_e32 v32, 0x3f4ccccd, v74
	s_waitcnt vmcnt(0)
	v_mul_f32_e32 v48, 0x3f4ccccd, v75
	v_mul_f32_e32 v67, v0, v67
	v_mul_f32_e32 v68, v16, v68
	v_mul_f32_e32 v69, v32, v69
	v_mul_f32_e32 v66, v48, v66
	v_bfe_u32 v70, v67, 16, 1
	v_bfe_u32 v71, v68, 16, 1
	v_bfe_u32 v72, v69, 16, 1
	v_bfe_u32 v73, v66, 16, 1
	v_add3_u32 v67, v67, v70, s75
	v_add3_u32 v68, v68, v71, s75
	v_add3_u32 v69, v69, v72, s75
	v_add3_u32 v66, v66, v73, s75
	v_lshrrev_b32_e32 v234, 6, v208
	v_lshlrev_b32_e32 v234, 13, v234
	v_bfe_u32 v235, v208, 5, 1
	v_lshl_add_u32 v234, v235, 10, v234
	v_and_b32_e32 v235, 31, v208
	v_lshl_add_u32 v234, v235, 1, v234
	v_mov_b32_e32 v236, v64
	v_mov_b32_e32 v237, v65
	ds_write_b16_d16_hi v234, v67 offset:36864
	ds_write_b16_d16_hi v234, v68 offset:36928
	ds_write_b16_d16_hi v234, v69 offset:36992
	ds_write_b16_d16_hi v234, v66 offset:37056
	v_mul_f32_e32 v66, v17, v17
	v_fmac_f32_e32 v66, v1, v1
	v_fmac_f32_e32 v66, v33, v33
	v_fmac_f32_e32 v66, v49, v49
	ds_bpermute_b32 v67, v154, v66
	s_waitcnt lgkmcnt(0)
	v_add_f32_e32 v66, v66, v67
	ds_bpermute_b32 v67, v155, v66
	s_waitcnt lgkmcnt(0)
	v_add_f32_e32 v66, v66, v67
	ds_bpermute_b32 v67, v156, v66
	s_waitcnt lgkmcnt(0)
	v_add_f32_e32 v66, v66, v67
	ds_bpermute_b32 v67, v157, v66
	s_waitcnt lgkmcnt(0)
	v_add_f32_e32 v66, v66, v67
	ds_bpermute_b32 v67, v158, v66
	s_waitcnt lgkmcnt(0)
	v_add_f32_e32 v66, v66, v67
	v_fmamk_f32 v66, v66, 0x3c000000, v160
	v_mul_f32_e32 v67, 0x4f800000, v66
	v_cmp_gt_f32_e32 vcc, s74, v66
	s_nop 1
	v_cndmask_b32_e32 v68, v66, v67, vcc
	v_sqrt_f32_e32 v69, v68
	v_add_co_u32_e64 v66, s[4:5], s59, v64
	v_add_u32_e32 v70, -1, v69
	s_nop 0
	v_addc_co_u32_e64 v67, s[4:5], 0, v65, s[4:5]
	v_add_u32_e32 v71, 1, v69
	v_fma_f32 v72, -v70, v69, v68
	v_fma_f32 v73, -v71, v69, v68
	v_cmp_ge_f32_e64 s[4:5], 0, v72
	s_nop 1
	v_cndmask_b32_e64 v69, v69, v70, s[4:5]
	v_cmp_lt_f32_e64 s[4:5], 0, v73
	s_nop 1
	v_cndmask_b32_e64 v69, v69, v71, s[4:5]
	v_mul_f32_e32 v70, 0x37800000, v69
	v_cndmask_b32_e32 v69, v69, v70, vcc
	v_cmp_class_f32_e32 vcc, v68, v161
	s_nop 1
	v_cndmask_b32_e32 v70, v69, v68, vcc
	v_div_scale_f32 v71, s[4:5], v70, v70, 1.0
	v_rcp_f32_e32 v72, v71
	v_add_co_u32_e32 v68, vcc, s76, v64
	v_fma_f32 v74, -v71, v72, 1.0
	s_nop 0
	v_addc_co_u32_e32 v69, vcc, 0, v65, vcc
	v_div_scale_f32 v73, vcc, 1.0, v70, 1.0
	v_fmac_f32_e32 v72, v74, v72
	v_mul_f32_e32 v74, v73, v72
	v_fma_f32 v75, -v71, v74, v73
	v_fmac_f32_e32 v74, v75, v72
	v_fma_f32 v71, -v71, v74, v73
	v_div_fmas_f32 v71, v71, v72, v74
	v_div_fixup_f32 v70, v71, v70, 1.0
	v_mul_f32_e32 v1, v1, v70
	v_mul_f32_e32 v17, v17, v70
	v_mul_f32_e32 v33, v33, v70
	v_mul_f32_e32 v1, v0, v1
	v_mul_f32_e32 v17, v16, v17
	v_mul_f32_e32 v33, v32, v33
	v_bfe_u32 v71, v1, 16, 1
	v_bfe_u32 v72, v17, 16, 1
	v_bfe_u32 v73, v33, 16, 1
	v_add3_u32 v1, v1, v71, s75
	v_add3_u32 v17, v17, v72, s75
	ds_write_b16_d16_hi v234, v1 offset:37120
	ds_write_b16_d16_hi v234, v17 offset:37184
	v_add3_u32 v1, v33, v73, s75
	ds_write_b16_d16_hi v234, v1 offset:37248
	v_mul_f32_e32 v1, v49, v70
	v_mul_f32_e32 v1, v48, v1
	v_bfe_u32 v17, v1, 16, 1
	v_add3_u32 v1, v1, v17, s75
	ds_write_b16_d16_hi v234, v1 offset:37312
	v_mul_f32_e32 v1, v18, v18
	v_fmac_f32_e32 v1, v2, v2
	v_fmac_f32_e32 v1, v34, v34
	v_fmac_f32_e32 v1, v50, v50
	ds_bpermute_b32 v17, v154, v1
	s_waitcnt lgkmcnt(0)
	v_add_f32_e32 v1, v1, v17
	ds_bpermute_b32 v17, v155, v1
	s_waitcnt lgkmcnt(0)
	v_add_f32_e32 v1, v1, v17
	ds_bpermute_b32 v17, v156, v1
	s_waitcnt lgkmcnt(0)
	v_add_f32_e32 v1, v1, v17
	ds_bpermute_b32 v17, v157, v1
	s_waitcnt lgkmcnt(0)
	v_add_f32_e32 v1, v1, v17
	ds_bpermute_b32 v17, v158, v1
	s_waitcnt lgkmcnt(0)
; #define SBAR() __builtin_amdgcn_sched_barrier(0)
; __device__ __forceinline__ int crow(int r, int hi) { return (r & 3) + 8 * (r >> 2) + 4 * hi; }
; __device__ __forceinline__ unsigned short f2bf(float f) { unsigned u = __float_as_uint(f); return (unsigned short)((u + 0x7fffu + ((u >> 16) & 1u)) >> 16); }
; __device__ __forceinline__ unsigned f2bf(float f) { unsigned u = __float_as_uint(f); return (u + 0x7fffu + ((u >> 16) & 1u)) >> 16; }
; template <bool DIFF> ...
;     ...
;     for (int r = 0; r < 16; ++r) {
;       float ss = o[0][r] * o[0][r] + o[1][r] * o[1][r] + o[2][r] * o[2][r] + o[3][r] * o[3][r];
;       ss += __shfl_xor(ss, 1); ss += __shfl_xor(ss, 2); ss += __shfl_xor(ss, 4); ss += __shfl_xor(ss, 8); ss += __shfl_xor(ss, 16);
;       const float rs = 1.0f / sqrtf(ss * (1.0f / 128.0f) + 1e-6f);
;       bf16* orow = Ow + (size_t)crow(r, hi) * 2048 + r32;
; #pragma unroll
;       for (int d = 0; d < 4; ++d) orow[32 * d] = f2bf(o[d][r] * rs * gsub[d]);
;       asm volatile("" ::: "memory"); SBAR();
	v_add_f32_e32 v1, v1, v17
	v_fmamk_f32 v1, v1, 0x3c000000, v160
	v_mul_f32_e32 v17, 0x4f800000, v1
	v_cmp_gt_f32_e32 vcc, s74, v1
	s_nop 1
	v_cndmask_b32_e32 v1, v1, v17, vcc
	v_sqrt_f32_e32 v17, v1
	s_nop 0
	v_add_u32_e32 v33, -1, v17
	v_add_u32_e32 v49, 1, v17
	v_fma_f32 v66, -v33, v17, v1
	v_fma_f32 v67, -v49, v17, v1
	v_cmp_ge_f32_e64 s[4:5], 0, v66
	s_nop 1
	v_cndmask_b32_e64 v17, v17, v33, s[4:5]
	v_cmp_lt_f32_e64 s[4:5], 0, v67
	s_nop 1
	v_cndmask_b32_e64 v17, v17, v49, s[4:5]
	v_mul_f32_e32 v33, 0x37800000, v17
	v_cndmask_b32_e32 v17, v17, v33, vcc
	v_cmp_class_f32_e32 vcc, v1, v161
	s_nop 1
	v_cndmask_b32_e32 v1, v17, v1, vcc
	v_div_scale_f32 v17, s[4:5], v1, v1, 1.0
	v_rcp_f32_e32 v33, v17
	v_div_scale_f32 v49, vcc, 1.0, v1, 1.0
	v_fma_f32 v66, -v17, v33, 1.0
	v_fmac_f32_e32 v33, v66, v33
	v_mul_f32_e32 v66, v49, v33
	v_fma_f32 v67, -v17, v66, v49
	v_fmac_f32_e32 v66, v67, v33
	v_fma_f32 v17, -v17, v66, v49
	v_div_fmas_f32 v17, v17, v33, v66
	v_div_fixup_f32 v1, v17, v1, 1.0
	v_mul_f32_e32 v2, v2, v1
	v_mul_f32_e32 v17, v18, v1
	v_mul_f32_e32 v18, v34, v1
	v_mul_f32_e32 v1, v50, v1
	v_mul_f32_e32 v2, v0, v2
	v_mul_f32_e32 v17, v16, v17
	v_mul_f32_e32 v18, v32, v18
	v_mul_f32_e32 v1, v48, v1
	v_bfe_u32 v33, v2, 16, 1
	v_bfe_u32 v34, v17, 16, 1
	v_bfe_u32 v49, v18, 16, 1
	v_bfe_u32 v50, v1, 16, 1
	v_add3_u32 v2, v2, v33, s75
	v_add3_u32 v17, v17, v34, s75
	v_add3_u32 v18, v18, v49, s75
	v_add3_u32 v1, v1, v50, s75
	ds_write_b16_d16_hi v234, v2 offset:37376
	ds_write_b16_d16_hi v234, v17 offset:37440
	ds_write_b16_d16_hi v234, v18 offset:37504
	ds_write_b16_d16_hi v234, v1 offset:37568
	v_mul_f32_e32 v1, v19, v19
	v_fmac_f32_e32 v1, v3, v3
	v_fmac_f32_e32 v1, v35, v35
	v_fmac_f32_e32 v1, v51, v51
	ds_bpermute_b32 v2, v154, v1
	s_waitcnt lgkmcnt(0)
	v_add_f32_e32 v1, v1, v2
	ds_bpermute_b32 v2, v155, v1
	s_waitcnt lgkmcnt(0)
	v_add_f32_e32 v1, v1, v2
	ds_bpermute_b32 v2, v156, v1
	s_waitcnt lgkmcnt(0)
	v_add_f32_e32 v1, v1, v2
	ds_bpermute_b32 v2, v157, v1
	s_waitcnt lgkmcnt(0)
	v_add_f32_e32 v1, v1, v2
	ds_bpermute_b32 v2, v158, v1
	s_waitcnt lgkmcnt(0)
	v_add_f32_e32 v1, v1, v2
	v_fmamk_f32 v1, v1, 0x3c000000, v160
	v_mul_f32_e32 v2, 0x4f800000, v1
	v_cmp_gt_f32_e32 vcc, s74, v1
	s_nop 1
	v_cndmask_b32_e32 v1, v1, v2, vcc
	v_sqrt_f32_e32 v2, v1
	s_nop 0
	v_add_u32_e32 v17, -1, v2
	v_add_u32_e32 v18, 1, v2
	v_fma_f32 v33, -v17, v2, v1
	v_fma_f32 v34, -v18, v2, v1
	v_cmp_ge_f32_e64 s[4:5], 0, v33
	s_nop 1
	v_cndmask_b32_e64 v2, v2, v17, s[4:5]
	v_cmp_lt_f32_e64 s[4:5], 0, v34
	s_nop 1
	v_cndmask_b32_e64 v2, v2, v18, s[4:5]
	v_mul_f32_e32 v17, 0x37800000, v2
	v_cndmask_b32_e32 v2, v2, v17, vcc
	v_cmp_class_f32_e32 vcc, v1, v161
	s_nop 1
	v_cndmask_b32_e32 v1, v2, v1, vcc
	v_div_scale_f32 v2, s[4:5], v1, v1, 1.0
	v_rcp_f32_e32 v17, v2
	v_add_co_u32_e32 v66, vcc, s77, v64
	v_fma_f32 v33, -v2, v17, 1.0
	s_nop 0
	v_addc_co_u32_e32 v67, vcc, 0, v65, vcc
	v_div_scale_f32 v18, vcc, 1.0, v1, 1.0
	v_fmac_f32_e32 v17, v33, v17
	v_mul_f32_e32 v33, v18, v17
	v_fma_f32 v34, -v2, v33, v18
	v_fmac_f32_e32 v33, v34, v17
	v_fma_f32 v2, -v2, v33, v18
	v_div_fmas_f32 v2, v2, v17, v33
	v_div_fixup_f32 v1, v2, v1, 1.0
	v_mul_f32_e32 v2, v3, v1
	v_mul_f32_e32 v3, v19, v1
	v_mul_f32_e32 v17, v35, v1
	v_mul_f32_e32 v2, v0, v2
	v_mul_f32_e32 v1, v51, v1
	v_mul_f32_e32 v3, v16, v3
	v_mul_f32_e32 v17, v32, v17
	v_bfe_u32 v18, v2, 16, 1
	v_mul_f32_e32 v1, v48, v1
	v_bfe_u32 v19, v3, 16, 1
	v_bfe_u32 v33, v17, 16, 1
	v_add3_u32 v2, v2, v18, s75
	v_add3_u32 v3, v3, v19, s75
	v_add3_u32 v17, v17, v33, s75
	ds_write_b16_d16_hi v234, v2 offset:37632
	ds_write_b16_d16_hi v234, v3 offset:37696
	ds_write_b16_d16_hi v234, v17 offset:37760
	v_bfe_u32 v2, v1, 16, 1
	v_add3_u32 v1, v1, v2, s75
	ds_write_b16_d16_hi v234, v1 offset:37824
	v_mul_f32_e32 v1, v20, v20
	v_fmac_f32_e32 v1, v4, v4
	v_fmac_f32_e32 v1, v36, v36
	v_fmac_f32_e32 v1, v52, v52
	ds_bpermute_b32 v2, v154, v1
	s_waitcnt lgkmcnt(0)
	v_add_f32_e32 v1, v1, v2
	ds_bpermute_b32 v2, v155, v1
	s_waitcnt lgkmcnt(0)
	v_add_f32_e32 v1, v1, v2
	ds_bpermute_b32 v2, v156, v1
	s_waitcnt lgkmcnt(0)
	v_add_f32_e32 v1, v1, v2
	ds_bpermute_b32 v2, v157, v1
	s_waitcnt lgkmcnt(0)
	v_add_f32_e32 v1, v1, v2
	ds_bpermute_b32 v2, v158, v1
	s_waitcnt lgkmcnt(0)
	v_add_f32_e32 v1, v1, v2
	v_fmamk_f32 v1, v1, 0x3c000000, v160
	v_mul_f32_e32 v2, 0x4f800000, v1
	v_cmp_gt_f32_e32 vcc, s74, v1
	s_nop 1
	v_cndmask_b32_e32 v1, v1, v2, vcc
	v_sqrt_f32_e32 v17, v1
	v_add_co_u32_e64 v2, s[4:5], s54, v64
	v_add_u32_e32 v18, -1, v17
	s_nop 0
	v_addc_co_u32_e64 v3, s[4:5], 0, v65, s[4:5]
	v_add_u32_e32 v19, 1, v17
	v_fma_f32 v33, -v18, v17, v1
	v_fma_f32 v34, -v19, v17, v1
	v_cmp_ge_f32_e64 s[4:5], 0, v33
	s_nop 1
	v_cndmask_b32_e64 v17, v17, v18, s[4:5]
	v_cmp_lt_f32_e64 s[4:5], 0, v34
	s_nop 1
	v_cndmask_b32_e64 v17, v17, v19, s[4:5]
	v_mul_f32_e32 v18, 0x37800000, v17
	v_cndmask_b32_e32 v17, v17, v18, vcc
	v_cmp_class_f32_e32 vcc, v1, v161
	s_nop 1
	v_cndmask_b32_e32 v1, v17, v1, vcc
	v_div_scale_f32 v17, s[4:5], v1, v1, 1.0
	v_rcp_f32_e32 v33, v17
	v_add_co_u32_e32 v18, vcc, s78, v64
	v_fma_f32 v35, -v17, v33, 1.0
	s_nop 0
	v_addc_co_u32_e32 v19, vcc, 0, v65, vcc
	v_div_scale_f32 v34, vcc, 1.0, v1, 1.0
	v_fmac_f32_e32 v33, v35, v33
	v_mul_f32_e32 v35, v34, v33
	v_fma_f32 v49, -v17, v35, v34
	v_fmac_f32_e32 v35, v49, v33
	v_fma_f32 v17, -v17, v35, v34
	v_div_fmas_f32 v17, v17, v33, v35
	v_div_fixup_f32 v1, v17, v1, 1.0
	v_mul_f32_e32 v4, v4, v1
	v_mul_f32_e32 v17, v20, v1
	v_mul_f32_e32 v20, v36, v1
	v_mul_f32_e32 v4, v0, v4
	v_mul_f32_e32 v17, v16, v17
	v_mul_f32_e32 v20, v32, v20
	v_bfe_u32 v33, v4, 16, 1
	v_bfe_u32 v34, v17, 16, 1
	v_bfe_u32 v35, v20, 16, 1
	v_add3_u32 v4, v4, v33, s75
	v_mul_f32_e32 v1, v52, v1
	v_add3_u32 v17, v17, v34, s75
	ds_write_b16_d16_hi v234, v4 offset:38912
	ds_write_b16_d16_hi v234, v17 offset:38976
	v_add3_u32 v4, v20, v35, s75
	v_mul_f32_e32 v1, v48, v1
	ds_write_b16_d16_hi v234, v4 offset:39040
	v_bfe_u32 v4, v1, 16, 1
	v_add3_u32 v1, v1, v4, s75
	ds_write_b16_d16_hi v234, v1 offset:39104
	v_mul_f32_e32 v1, v21, v21
	v_fmac_f32_e32 v1, v5, v5
	v_fmac_f32_e32 v1, v37, v37
	v_fmac_f32_e32 v1, v53, v53
	ds_bpermute_b32 v2, v154, v1
	s_waitcnt lgkmcnt(0)
; #define SBAR() __builtin_amdgcn_sched_barrier(0)
; __device__ __forceinline__ int crow(int r, int hi) { return (r & 3) + 8 * (r >> 2) + 4 * hi; }
; __device__ __forceinline__ unsigned short f2bf(float f) { unsigned u = __float_as_uint(f); return (unsigned short)((u + 0x7fffu + ((u >> 16) & 1u)) >> 16); }
; __device__ __forceinline__ unsigned f2bf(float f) { unsigned u = __float_as_uint(f); return (u + 0x7fffu + ((u >> 16) & 1u)) >> 16; }
; template <bool DIFF> ...
;     ...
;     for (int r = 0; r < 16; ++r) {
;       float ss = o[0][r] * o[0][r] + o[1][r] * o[1][r] + o[2][r] * o[2][r] + o[3][r] * o[3][r];
;       ss += __shfl_xor(ss, 1); ss += __shfl_xor(ss, 2); ss += __shfl_xor(ss, 4); ss += __shfl_xor(ss, 8); ss += __shfl_xor(ss, 16);
;       const float rs = 1.0f / sqrtf(ss * (1.0f / 128.0f) + 1e-6f);
;       bf16* orow = Ow + (size_t)crow(r, hi) * 2048 + r32;
; #pragma unroll
;       for (int d = 0; d < 4; ++d) orow[32 * d] = f2bf(o[d][r] * rs * gsub[d]);
;       asm volatile("" ::: "memory"); SBAR();
	v_add_f32_e32 v1, v1, v2
	ds_bpermute_b32 v2, v155, v1
	s_waitcnt lgkmcnt(0)
	v_add_f32_e32 v1, v1, v2
	ds_bpermute_b32 v2, v156, v1
	s_waitcnt lgkmcnt(0)
	v_add_f32_e32 v1, v1, v2
	ds_bpermute_b32 v2, v157, v1
	s_waitcnt lgkmcnt(0)
	v_add_f32_e32 v1, v1, v2
	ds_bpermute_b32 v2, v158, v1
	s_waitcnt lgkmcnt(0)
	v_add_f32_e32 v1, v1, v2
	v_fmamk_f32 v1, v1, 0x3c000000, v160
	v_mul_f32_e32 v2, 0x4f800000, v1
	v_cmp_gt_f32_e32 vcc, s74, v1
	s_nop 1
	v_cndmask_b32_e32 v1, v1, v2, vcc
	v_sqrt_f32_e32 v2, v1
	s_nop 0
	v_add_u32_e32 v3, -1, v2
	v_add_u32_e32 v4, 1, v2
	v_fma_f32 v17, -v3, v2, v1
	v_fma_f32 v20, -v4, v2, v1
	v_cmp_ge_f32_e64 s[4:5], 0, v17
	s_nop 1
	v_cndmask_b32_e64 v2, v2, v3, s[4:5]
	v_cmp_lt_f32_e64 s[4:5], 0, v20
	s_nop 1
	v_cndmask_b32_e64 v2, v2, v4, s[4:5]
	v_mul_f32_e32 v3, 0x37800000, v2
	v_cndmask_b32_e32 v2, v2, v3, vcc
	v_cmp_class_f32_e32 vcc, v1, v161
	s_nop 1
	v_cndmask_b32_e32 v1, v2, v1, vcc
	v_div_scale_f32 v2, s[4:5], v1, v1, 1.0
	v_rcp_f32_e32 v3, v2
	v_div_scale_f32 v4, vcc, 1.0, v1, 1.0
	v_fma_f32 v17, -v2, v3, 1.0
	v_fmac_f32_e32 v3, v17, v3
	v_mul_f32_e32 v17, v4, v3
	v_fma_f32 v20, -v2, v17, v4
	v_fmac_f32_e32 v17, v20, v3
	v_fma_f32 v2, -v2, v17, v4
	v_div_fmas_f32 v2, v2, v3, v17
	v_div_fixup_f32 v1, v2, v1, 1.0
	v_mul_f32_e32 v2, v5, v1
	v_mul_f32_e32 v3, v21, v1
	v_mul_f32_e32 v4, v37, v1
	v_mul_f32_e32 v1, v53, v1
	v_mul_f32_e32 v2, v0, v2
	v_mul_f32_e32 v3, v16, v3
	v_mul_f32_e32 v4, v32, v4
	v_mul_f32_e32 v1, v48, v1
	v_bfe_u32 v5, v2, 16, 1
	v_bfe_u32 v17, v3, 16, 1
	v_bfe_u32 v20, v4, 16, 1
	v_bfe_u32 v21, v1, 16, 1
	v_add3_u32 v2, v2, v5, s75
	v_add3_u32 v3, v3, v17, s75
	v_add3_u32 v4, v4, v20, s75
	v_add3_u32 v1, v1, v21, s75
	ds_write_b16_d16_hi v234, v2 offset:39168
	ds_write_b16_d16_hi v234, v3 offset:39232
	ds_write_b16_d16_hi v234, v4 offset:39296
	ds_write_b16_d16_hi v234, v1 offset:39360
	v_mul_f32_e32 v1, v22, v22
	v_fmac_f32_e32 v1, v6, v6
	v_fmac_f32_e32 v1, v38, v38
	v_fmac_f32_e32 v1, v54, v54
	ds_bpermute_b32 v2, v154, v1
	s_waitcnt lgkmcnt(0)
	v_add_f32_e32 v1, v1, v2
	ds_bpermute_b32 v2, v155, v1
	s_waitcnt lgkmcnt(0)
	v_add_f32_e32 v1, v1, v2
	ds_bpermute_b32 v2, v156, v1
	s_waitcnt lgkmcnt(0)
	v_add_f32_e32 v1, v1, v2
	ds_bpermute_b32 v2, v157, v1
	s_waitcnt lgkmcnt(0)
	v_add_f32_e32 v1, v1, v2
	ds_bpermute_b32 v2, v158, v1
	s_waitcnt lgkmcnt(0)
	v_add_f32_e32 v1, v1, v2
	v_fmamk_f32 v1, v1, 0x3c000000, v160
	v_mul_f32_e32 v2, 0x4f800000, v1
	v_cmp_gt_f32_e32 vcc, s74, v1
	s_nop 1
	v_cndmask_b32_e32 v1, v1, v2, vcc
	v_sqrt_f32_e32 v4, v1
	v_add_co_u32_e64 v2, s[4:5], s79, v64
	v_add_u32_e32 v5, -1, v4
	s_nop 0
	v_addc_co_u32_e64 v3, s[4:5], 0, v65, s[4:5]
	v_add_u32_e32 v17, 1, v4
	v_fma_f32 v18, -v5, v4, v1
	v_fma_f32 v19, -v17, v4, v1
	v_cmp_ge_f32_e64 s[4:5], 0, v18
	s_nop 1
	v_cndmask_b32_e64 v4, v4, v5, s[4:5]
	v_cmp_lt_f32_e64 s[4:5], 0, v19
	s_nop 1
	v_cndmask_b32_e64 v4, v4, v17, s[4:5]
	v_mul_f32_e32 v5, 0x37800000, v4
	v_cndmask_b32_e32 v4, v4, v5, vcc
	v_cmp_class_f32_e32 vcc, v1, v161
	s_nop 1
	v_cndmask_b32_e32 v1, v4, v1, vcc
	v_div_scale_f32 v17, s[4:5], v1, v1, 1.0
	v_rcp_f32_e32 v18, v17
	v_add_co_u32_e32 v4, vcc, s80, v64
	v_fma_f32 v20, -v17, v18, 1.0
	s_nop 0
	v_addc_co_u32_e32 v5, vcc, 0, v65, vcc
	v_div_scale_f32 v19, vcc, 1.0, v1, 1.0
	v_fmac_f32_e32 v18, v20, v18
	v_mul_f32_e32 v20, v19, v18
	v_fma_f32 v21, -v17, v20, v19
	v_fmac_f32_e32 v20, v21, v18
	v_fma_f32 v17, -v17, v20, v19
	v_div_fmas_f32 v17, v17, v18, v20
	v_div_fixup_f32 v1, v17, v1, 1.0
	v_mul_f32_e32 v6, v6, v1
	v_mul_f32_e32 v17, v22, v1
	v_mul_f32_e32 v18, v38, v1
	v_mul_f32_e32 v6, v0, v6
	v_mul_f32_e32 v17, v16, v17
	v_mul_f32_e32 v18, v32, v18
	v_bfe_u32 v19, v6, 16, 1
	v_bfe_u32 v20, v17, 16, 1
	v_bfe_u32 v21, v18, 16, 1
	v_add3_u32 v6, v6, v19, s75
	v_mul_f32_e32 v1, v54, v1
	v_add3_u32 v17, v17, v20, s75
	ds_write_b16_d16_hi v234, v6 offset:39424
	ds_write_b16_d16_hi v234, v17 offset:39488
	v_add3_u32 v6, v18, v21, s75
	v_mul_f32_e32 v1, v48, v1
	ds_write_b16_d16_hi v234, v6 offset:39552
	v_bfe_u32 v6, v1, 16, 1
	v_add3_u32 v1, v1, v6, s75
	ds_write_b16_d16_hi v234, v1 offset:39616
	v_mul_f32_e32 v1, v23, v23
	v_fmac_f32_e32 v1, v7, v7
	v_fmac_f32_e32 v1, v39, v39
	v_fmac_f32_e32 v1, v55, v55
	ds_bpermute_b32 v2, v154, v1
	s_waitcnt lgkmcnt(0)
	v_add_f32_e32 v1, v1, v2
	ds_bpermute_b32 v2, v155, v1
	s_waitcnt lgkmcnt(0)
	v_add_f32_e32 v1, v1, v2
	ds_bpermute_b32 v2, v156, v1
	s_waitcnt lgkmcnt(0)
	v_add_f32_e32 v1, v1, v2
	ds_bpermute_b32 v2, v157, v1
	s_waitcnt lgkmcnt(0)
	v_add_f32_e32 v1, v1, v2
	ds_bpermute_b32 v2, v158, v1
	s_waitcnt lgkmcnt(0)
	v_add_f32_e32 v1, v1, v2
	v_fmamk_f32 v1, v1, 0x3c000000, v160
	v_mul_f32_e32 v2, 0x4f800000, v1
	v_cmp_gt_f32_e32 vcc, s74, v1
	s_nop 1
	v_cndmask_b32_e32 v1, v1, v2, vcc
	v_sqrt_f32_e32 v2, v1
	s_nop 0
	v_add_u32_e32 v3, -1, v2
	v_add_u32_e32 v6, 1, v2
	v_fma_f32 v17, -v3, v2, v1
	v_fma_f32 v18, -v6, v2, v1
	v_cmp_ge_f32_e64 s[4:5], 0, v17
	s_nop 1
	v_cndmask_b32_e64 v2, v2, v3, s[4:5]
	v_cmp_lt_f32_e64 s[4:5], 0, v18
	s_nop 1
	v_cndmask_b32_e64 v2, v2, v6, s[4:5]
	v_mul_f32_e32 v3, 0x37800000, v2
	v_cndmask_b32_e32 v2, v2, v3, vcc
	v_cmp_class_f32_e32 vcc, v1, v161
	s_nop 1
	v_cndmask_b32_e32 v1, v2, v1, vcc
	v_div_scale_f32 v2, s[4:5], v1, v1, 1.0
	v_rcp_f32_e32 v3, v2
	v_div_scale_f32 v6, vcc, 1.0, v1, 1.0
	v_fma_f32 v17, -v2, v3, 1.0
	v_fmac_f32_e32 v3, v17, v3
	v_mul_f32_e32 v17, v6, v3
	v_fma_f32 v18, -v2, v17, v6
	v_fmac_f32_e32 v17, v18, v3
	v_fma_f32 v2, -v2, v17, v6
	v_div_fmas_f32 v2, v2, v3, v17
	v_div_fixup_f32 v1, v2, v1, 1.0
	v_mul_f32_e32 v2, v7, v1
	v_mul_f32_e32 v3, v23, v1
	v_mul_f32_e32 v6, v39, v1
	v_mul_f32_e32 v1, v55, v1
	v_mul_f32_e32 v2, v0, v2
	v_mul_f32_e32 v3, v16, v3
	v_mul_f32_e32 v6, v32, v6
	v_mul_f32_e32 v1, v48, v1
	v_bfe_u32 v7, v2, 16, 1
	v_bfe_u32 v17, v3, 16, 1
	v_bfe_u32 v18, v6, 16, 1
	v_bfe_u32 v19, v1, 16, 1
	v_add3_u32 v2, v2, v7, s75
	v_add3_u32 v3, v3, v17, s75
	v_add3_u32 v6, v6, v18, s75
	v_add3_u32 v1, v1, v19, s75
	ds_write_b16_d16_hi v234, v2 offset:39680
	ds_write_b16_d16_hi v234, v3 offset:39744
	ds_write_b16_d16_hi v234, v6 offset:39808
	ds_write_b16_d16_hi v234, v1 offset:39872
	v_mul_f32_e32 v1, v24, v24
	v_fmac_f32_e32 v1, v8, v8
	v_fmac_f32_e32 v1, v40, v40
	v_fmac_f32_e32 v1, v56, v56
	ds_bpermute_b32 v2, v154, v1
	s_waitcnt lgkmcnt(0)
; #define SBAR() __builtin_amdgcn_sched_barrier(0)
; __device__ __forceinline__ int crow(int r, int hi) { return (r & 3) + 8 * (r >> 2) + 4 * hi; }
; __device__ __forceinline__ unsigned short f2bf(float f) { unsigned u = __float_as_uint(f); return (unsigned short)((u + 0x7fffu + ((u >> 16) & 1u)) >> 16); }
; __device__ __forceinline__ unsigned f2bf(float f) { unsigned u = __float_as_uint(f); return (u + 0x7fffu + ((u >> 16) & 1u)) >> 16; }
; template <bool DIFF> ...
;     ...
;     for (int r = 0; r < 16; ++r) {
;       float ss = o[0][r] * o[0][r] + o[1][r] * o[1][r] + o[2][r] * o[2][r] + o[3][r] * o[3][r];
;       ss += __shfl_xor(ss, 1); ss += __shfl_xor(ss, 2); ss += __shfl_xor(ss, 4); ss += __shfl_xor(ss, 8); ss += __shfl_xor(ss, 16);
;       const float rs = 1.0f / sqrtf(ss * (1.0f / 128.0f) + 1e-6f);
;       bf16* orow = Ow + (size_t)crow(r, hi) * 2048 + r32;
; #pragma unroll
;       for (int d = 0; d < 4; ++d) orow[32 * d] = f2bf(o[d][r] * rs * gsub[d]);
;       asm volatile("" ::: "memory"); SBAR();
	v_add_f32_e32 v1, v1, v2
	ds_bpermute_b32 v2, v155, v1
	s_waitcnt lgkmcnt(0)
	v_add_f32_e32 v1, v1, v2
	ds_bpermute_b32 v2, v156, v1
	s_waitcnt lgkmcnt(0)
	v_add_f32_e32 v1, v1, v2
	ds_bpermute_b32 v2, v157, v1
	s_waitcnt lgkmcnt(0)
	v_add_f32_e32 v1, v1, v2
	ds_bpermute_b32 v2, v158, v1
	s_waitcnt lgkmcnt(0)
	v_add_f32_e32 v1, v1, v2
	v_fmamk_f32 v1, v1, 0x3c000000, v160
	v_mul_f32_e32 v2, 0x4f800000, v1
	v_cmp_gt_f32_e32 vcc, s74, v1
	s_nop 1
	v_cndmask_b32_e32 v1, v1, v2, vcc
	v_sqrt_f32_e32 v4, v1
	v_add_co_u32_e64 v2, s[4:5], s66, v64
	v_add_u32_e32 v5, -1, v4
	s_nop 0
	v_addc_co_u32_e64 v3, s[4:5], 0, v65, s[4:5]
	v_add_u32_e32 v6, 1, v4
	v_fma_f32 v7, -v5, v4, v1
	v_fma_f32 v17, -v6, v4, v1
	v_cmp_ge_f32_e64 s[4:5], 0, v7
	s_nop 1
	v_cndmask_b32_e64 v4, v4, v5, s[4:5]
	v_cmp_lt_f32_e64 s[4:5], 0, v17
	s_nop 1
	v_cndmask_b32_e64 v4, v4, v6, s[4:5]
	v_mul_f32_e32 v5, 0x37800000, v4
	v_cndmask_b32_e32 v4, v4, v5, vcc
	v_cmp_class_f32_e32 vcc, v1, v161
	s_nop 1
	v_cndmask_b32_e32 v1, v4, v1, vcc
	v_div_scale_f32 v6, s[4:5], v1, v1, 1.0
	v_rcp_f32_e32 v7, v6
	v_add_co_u32_e32 v4, vcc, s81, v64
	v_fma_f32 v18, -v6, v7, 1.0
	s_nop 0
	v_addc_co_u32_e32 v5, vcc, 0, v65, vcc
	v_div_scale_f32 v17, vcc, 1.0, v1, 1.0
	v_fmac_f32_e32 v7, v18, v7
	v_mul_f32_e32 v18, v17, v7
	v_fma_f32 v19, -v6, v18, v17
	v_fmac_f32_e32 v18, v19, v7
	v_fma_f32 v6, -v6, v18, v17
	v_div_fmas_f32 v6, v6, v7, v18
	v_div_fixup_f32 v1, v6, v1, 1.0
	v_mul_f32_e32 v6, v8, v1
	v_mul_f32_e32 v7, v24, v1
	v_mul_f32_e32 v8, v40, v1
	v_mul_f32_e32 v6, v0, v6
	v_mul_f32_e32 v7, v16, v7
	v_mul_f32_e32 v8, v32, v8
	v_bfe_u32 v17, v6, 16, 1
	v_bfe_u32 v18, v7, 16, 1
	v_bfe_u32 v19, v8, 16, 1
	v_add3_u32 v6, v6, v17, s75
	v_mul_f32_e32 v1, v56, v1
	v_add3_u32 v7, v7, v18, s75
	ds_write_b16_d16_hi v234, v6 offset:40960
	ds_write_b16_d16_hi v234, v7 offset:41024
	v_add3_u32 v6, v8, v19, s75
	v_mul_f32_e32 v1, v48, v1
	ds_write_b16_d16_hi v234, v6 offset:41088
	v_bfe_u32 v6, v1, 16, 1
	v_add3_u32 v1, v1, v6, s75
	ds_write_b16_d16_hi v234, v1 offset:41152
	v_mul_f32_e32 v1, v25, v25
	v_fmac_f32_e32 v1, v9, v9
	v_fmac_f32_e32 v1, v41, v41
	v_fmac_f32_e32 v1, v57, v57
	ds_bpermute_b32 v2, v154, v1
	s_waitcnt lgkmcnt(0)
	v_add_f32_e32 v1, v1, v2
	ds_bpermute_b32 v2, v155, v1
	s_waitcnt lgkmcnt(0)
	v_add_f32_e32 v1, v1, v2
	ds_bpermute_b32 v2, v156, v1
	s_waitcnt lgkmcnt(0)
	v_add_f32_e32 v1, v1, v2
	ds_bpermute_b32 v2, v157, v1
	s_waitcnt lgkmcnt(0)
	v_add_f32_e32 v1, v1, v2
	ds_bpermute_b32 v2, v158, v1
	s_waitcnt lgkmcnt(0)
	v_add_f32_e32 v1, v1, v2
	v_fmamk_f32 v1, v1, 0x3c000000, v160
	v_mul_f32_e32 v2, 0x4f800000, v1
	v_cmp_gt_f32_e32 vcc, s74, v1
	s_nop 1
	v_cndmask_b32_e32 v1, v1, v2, vcc
	v_sqrt_f32_e32 v2, v1
	s_nop 0
	v_add_u32_e32 v3, -1, v2
	v_add_u32_e32 v6, 1, v2
	v_fma_f32 v7, -v3, v2, v1
	v_fma_f32 v8, -v6, v2, v1
	v_cmp_ge_f32_e64 s[4:5], 0, v7
	s_nop 1
	v_cndmask_b32_e64 v2, v2, v3, s[4:5]
	v_cmp_lt_f32_e64 s[4:5], 0, v8
	s_nop 1
	v_cndmask_b32_e64 v2, v2, v6, s[4:5]
	v_mul_f32_e32 v3, 0x37800000, v2
	v_cndmask_b32_e32 v2, v2, v3, vcc
	v_cmp_class_f32_e32 vcc, v1, v161
	s_nop 1
	v_cndmask_b32_e32 v1, v2, v1, vcc
	v_div_scale_f32 v2, s[4:5], v1, v1, 1.0
	v_rcp_f32_e32 v3, v2
	v_div_scale_f32 v6, vcc, 1.0, v1, 1.0
	v_fma_f32 v7, -v2, v3, 1.0
	v_fmac_f32_e32 v3, v7, v3
	v_mul_f32_e32 v7, v6, v3
	v_fma_f32 v8, -v2, v7, v6
	v_fmac_f32_e32 v7, v8, v3
	v_fma_f32 v2, -v2, v7, v6
	v_div_fmas_f32 v2, v2, v3, v7
	v_div_fixup_f32 v1, v2, v1, 1.0
	v_mul_f32_e32 v2, v9, v1
	v_mul_f32_e32 v3, v25, v1
	v_mul_f32_e32 v6, v41, v1
	v_mul_f32_e32 v1, v57, v1
	v_mul_f32_e32 v2, v0, v2
	v_mul_f32_e32 v3, v16, v3
	v_mul_f32_e32 v6, v32, v6
	v_mul_f32_e32 v1, v48, v1
	v_bfe_u32 v7, v2, 16, 1
	v_bfe_u32 v8, v3, 16, 1
	v_bfe_u32 v9, v6, 16, 1
	v_bfe_u32 v17, v1, 16, 1
	v_add3_u32 v2, v2, v7, s75
	v_add3_u32 v3, v3, v8, s75
	v_add3_u32 v6, v6, v9, s75
	v_add3_u32 v1, v1, v17, s75
	ds_write_b16_d16_hi v234, v2 offset:41216
	ds_write_b16_d16_hi v234, v3 offset:41280
	ds_write_b16_d16_hi v234, v6 offset:41344
	ds_write_b16_d16_hi v234, v1 offset:41408
	v_mul_f32_e32 v1, v26, v26
	v_fmac_f32_e32 v1, v10, v10
	v_fmac_f32_e32 v1, v42, v42
	v_fmac_f32_e32 v1, v58, v58
	ds_bpermute_b32 v2, v154, v1
	s_waitcnt lgkmcnt(0)
	v_add_f32_e32 v1, v1, v2
	ds_bpermute_b32 v2, v155, v1
	s_waitcnt lgkmcnt(0)
	v_add_f32_e32 v1, v1, v2
	ds_bpermute_b32 v2, v156, v1
	s_waitcnt lgkmcnt(0)
	v_add_f32_e32 v1, v1, v2
	ds_bpermute_b32 v2, v157, v1
	s_waitcnt lgkmcnt(0)
	v_add_f32_e32 v1, v1, v2
	ds_bpermute_b32 v2, v158, v1
	s_waitcnt lgkmcnt(0)
	v_add_f32_e32 v1, v1, v2
	v_fmamk_f32 v1, v1, 0x3c000000, v160
	v_mul_f32_e32 v2, 0x4f800000, v1
	v_cmp_gt_f32_e32 vcc, s74, v1
	s_nop 1
	v_cndmask_b32_e32 v1, v1, v2, vcc
	v_sqrt_f32_e32 v4, v1
	v_add_co_u32_e64 v2, s[4:5], s82, v64
	v_add_u32_e32 v5, -1, v4
	s_nop 0
	v_addc_co_u32_e64 v3, s[4:5], 0, v65, s[4:5]
	v_add_u32_e32 v6, 1, v4
	v_fma_f32 v7, -v5, v4, v1
	v_fma_f32 v8, -v6, v4, v1
	v_cmp_ge_f32_e64 s[4:5], 0, v7
	s_nop 1
	v_cndmask_b32_e64 v4, v4, v5, s[4:5]
	v_cmp_lt_f32_e64 s[4:5], 0, v8
	s_nop 1
	v_cndmask_b32_e64 v4, v4, v6, s[4:5]
	v_mul_f32_e32 v5, 0x37800000, v4
	v_cndmask_b32_e32 v4, v4, v5, vcc
	v_cmp_class_f32_e32 vcc, v1, v161
	s_nop 1
	v_cndmask_b32_e32 v1, v4, v1, vcc
	v_div_scale_f32 v6, s[4:5], v1, v1, 1.0
	v_rcp_f32_e32 v7, v6
	v_add_co_u32_e32 v4, vcc, s83, v64
	v_fma_f32 v9, -v6, v7, 1.0
	s_nop 0
	v_addc_co_u32_e32 v5, vcc, 0, v65, vcc
	v_div_scale_f32 v8, vcc, 1.0, v1, 1.0
	v_fmac_f32_e32 v7, v9, v7
	v_mul_f32_e32 v9, v8, v7
	v_fma_f32 v17, -v6, v9, v8
	v_fmac_f32_e32 v9, v17, v7
	v_fma_f32 v6, -v6, v9, v8
	v_div_fmas_f32 v6, v6, v7, v9
	v_div_fixup_f32 v1, v6, v1, 1.0
	v_mul_f32_e32 v6, v10, v1
	v_mul_f32_e32 v7, v26, v1
	v_mul_f32_e32 v8, v42, v1
	v_mul_f32_e32 v6, v0, v6
	v_mul_f32_e32 v7, v16, v7
	v_mul_f32_e32 v8, v32, v8
	v_bfe_u32 v9, v6, 16, 1
	v_bfe_u32 v10, v7, 16, 1
	v_bfe_u32 v17, v8, 16, 1
	v_add3_u32 v6, v6, v9, s75
	v_mul_f32_e32 v1, v58, v1
	v_add3_u32 v7, v7, v10, s75
	ds_write_b16_d16_hi v234, v6 offset:41472
	ds_write_b16_d16_hi v234, v7 offset:41536
	v_add3_u32 v6, v8, v17, s75
	v_mul_f32_e32 v1, v48, v1
	ds_write_b16_d16_hi v234, v6 offset:41600
	v_bfe_u32 v6, v1, 16, 1
	v_add3_u32 v1, v1, v6, s75
	ds_write_b16_d16_hi v234, v1 offset:41664
	v_mul_f32_e32 v1, v27, v27
	v_fmac_f32_e32 v1, v11, v11
	v_fmac_f32_e32 v1, v43, v43
	v_fmac_f32_e32 v1, v59, v59
	ds_bpermute_b32 v2, v154, v1
	s_waitcnt lgkmcnt(0)
; #define SBAR() __builtin_amdgcn_sched_barrier(0)
; __device__ __forceinline__ int crow(int r, int hi) { return (r & 3) + 8 * (r >> 2) + 4 * hi; }
; __device__ __forceinline__ unsigned short f2bf(float f) { unsigned u = __float_as_uint(f); return (unsigned short)((u + 0x7fffu + ((u >> 16) & 1u)) >> 16); }
; __device__ __forceinline__ unsigned f2bf(float f) { unsigned u = __float_as_uint(f); return (u + 0x7fffu + ((u >> 16) & 1u)) >> 16; }
; template <bool DIFF> ...
;     ...
;     for (int r = 0; r < 16; ++r) {
;       float ss = o[0][r] * o[0][r] + o[1][r] * o[1][r] + o[2][r] * o[2][r] + o[3][r] * o[3][r];
;       ss += __shfl_xor(ss, 1); ss += __shfl_xor(ss, 2); ss += __shfl_xor(ss, 4); ss += __shfl_xor(ss, 8); ss += __shfl_xor(ss, 16);
;       const float rs = 1.0f / sqrtf(ss * (1.0f / 128.0f) + 1e-6f);
;       bf16* orow = Ow + (size_t)crow(r, hi) * 2048 + r32;
; #pragma unroll
;       for (int d = 0; d < 4; ++d) orow[32 * d] = f2bf(o[d][r] * rs * gsub[d]);
;       asm volatile("" ::: "memory"); SBAR();
	v_add_f32_e32 v1, v1, v2
	ds_bpermute_b32 v2, v155, v1
	s_waitcnt lgkmcnt(0)
	v_add_f32_e32 v1, v1, v2
	ds_bpermute_b32 v2, v156, v1
	s_waitcnt lgkmcnt(0)
	v_add_f32_e32 v1, v1, v2
	ds_bpermute_b32 v2, v157, v1
	s_waitcnt lgkmcnt(0)
	v_add_f32_e32 v1, v1, v2
	ds_bpermute_b32 v2, v158, v1
	s_waitcnt lgkmcnt(0)
	v_add_f32_e32 v1, v1, v2
	v_fmamk_f32 v1, v1, 0x3c000000, v160
	v_mul_f32_e32 v2, 0x4f800000, v1
	v_cmp_gt_f32_e32 vcc, s74, v1
	s_nop 1
	v_cndmask_b32_e32 v1, v1, v2, vcc
	v_sqrt_f32_e32 v2, v1
	s_nop 0
	v_add_u32_e32 v3, -1, v2
	v_add_u32_e32 v6, 1, v2
	v_fma_f32 v7, -v3, v2, v1
	v_fma_f32 v8, -v6, v2, v1
	v_cmp_ge_f32_e64 s[4:5], 0, v7
	s_nop 1
	v_cndmask_b32_e64 v2, v2, v3, s[4:5]
	v_cmp_lt_f32_e64 s[4:5], 0, v8
	s_nop 1
	v_cndmask_b32_e64 v2, v2, v6, s[4:5]
	v_mul_f32_e32 v3, 0x37800000, v2
	v_cndmask_b32_e32 v2, v2, v3, vcc
	v_cmp_class_f32_e32 vcc, v1, v161
	s_nop 1
	v_cndmask_b32_e32 v1, v2, v1, vcc
	v_div_scale_f32 v2, s[4:5], v1, v1, 1.0
	v_rcp_f32_e32 v3, v2
	v_div_scale_f32 v6, vcc, 1.0, v1, 1.0
	v_fma_f32 v7, -v2, v3, 1.0
	v_fmac_f32_e32 v3, v7, v3
	v_mul_f32_e32 v7, v6, v3
	v_fma_f32 v8, -v2, v7, v6
	v_fmac_f32_e32 v7, v8, v3
	v_fma_f32 v2, -v2, v7, v6
	v_div_fmas_f32 v2, v2, v3, v7
	v_div_fixup_f32 v1, v2, v1, 1.0
	v_mul_f32_e32 v2, v11, v1
	v_mul_f32_e32 v3, v27, v1
	v_mul_f32_e32 v6, v43, v1
	v_mul_f32_e32 v1, v59, v1
	v_mul_f32_e32 v2, v0, v2
	v_mul_f32_e32 v3, v16, v3
	v_mul_f32_e32 v6, v32, v6
	v_mul_f32_e32 v1, v48, v1
	v_bfe_u32 v7, v2, 16, 1
	v_bfe_u32 v8, v3, 16, 1
	v_bfe_u32 v9, v6, 16, 1
	v_bfe_u32 v10, v1, 16, 1
	v_add3_u32 v2, v2, v7, s75
	v_add3_u32 v3, v3, v8, s75
	v_add3_u32 v6, v6, v9, s75
	v_add3_u32 v1, v1, v10, s75
	ds_write_b16_d16_hi v234, v2 offset:41728
	ds_write_b16_d16_hi v234, v3 offset:41792
	ds_write_b16_d16_hi v234, v6 offset:41856
	ds_write_b16_d16_hi v234, v1 offset:41920
	v_mul_f32_e32 v1, v28, v28
	v_fmac_f32_e32 v1, v12, v12
	v_fmac_f32_e32 v1, v44, v44
	v_fmac_f32_e32 v1, v60, v60
	ds_bpermute_b32 v2, v154, v1
	s_waitcnt lgkmcnt(0)
	v_add_f32_e32 v1, v1, v2
	ds_bpermute_b32 v2, v155, v1
	s_waitcnt lgkmcnt(0)
	v_add_f32_e32 v1, v1, v2
	ds_bpermute_b32 v2, v156, v1
	s_waitcnt lgkmcnt(0)
	v_add_f32_e32 v1, v1, v2
	ds_bpermute_b32 v2, v157, v1
	s_waitcnt lgkmcnt(0)
	v_add_f32_e32 v1, v1, v2
	ds_bpermute_b32 v2, v158, v1
	s_waitcnt lgkmcnt(0)
	v_add_f32_e32 v1, v1, v2
	v_fmamk_f32 v1, v1, 0x3c000000, v160
	v_mul_f32_e32 v2, 0x4f800000, v1
	v_cmp_gt_f32_e32 vcc, s74, v1
	s_nop 1
	v_cndmask_b32_e32 v1, v1, v2, vcc
	v_sqrt_f32_e32 v4, v1
	v_add_co_u32_e64 v2, s[4:5], s84, v64
	v_add_u32_e32 v5, -1, v4
	s_nop 0
	v_addc_co_u32_e64 v3, s[4:5], 0, v65, s[4:5]
	v_add_u32_e32 v6, 1, v4
	v_fma_f32 v7, -v5, v4, v1
	v_fma_f32 v8, -v6, v4, v1
	v_cmp_ge_f32_e64 s[4:5], 0, v7
	s_nop 1
	v_cndmask_b32_e64 v4, v4, v5, s[4:5]
	v_cmp_lt_f32_e64 s[4:5], 0, v8
	s_nop 1
	v_cndmask_b32_e64 v4, v4, v6, s[4:5]
	v_mul_f32_e32 v5, 0x37800000, v4
	v_cndmask_b32_e32 v4, v4, v5, vcc
	v_cmp_class_f32_e32 vcc, v1, v161
	s_nop 1
	v_cndmask_b32_e32 v1, v4, v1, vcc
	v_div_scale_f32 v6, s[4:5], v1, v1, 1.0
	v_rcp_f32_e32 v7, v6
	v_add_co_u32_e32 v4, vcc, s85, v64
	v_fma_f32 v9, -v6, v7, 1.0
	s_nop 0
	v_addc_co_u32_e32 v5, vcc, 0, v65, vcc
	v_div_scale_f32 v8, vcc, 1.0, v1, 1.0
	v_fmac_f32_e32 v7, v9, v7
	v_mul_f32_e32 v9, v8, v7
	v_fma_f32 v10, -v6, v9, v8
	v_fmac_f32_e32 v9, v10, v7
	v_fma_f32 v6, -v6, v9, v8
	v_div_fmas_f32 v6, v6, v7, v9
	v_div_fixup_f32 v1, v6, v1, 1.0
	v_mul_f32_e32 v6, v12, v1
	v_mul_f32_e32 v7, v28, v1
	v_mul_f32_e32 v8, v44, v1
	v_mul_f32_e32 v6, v0, v6
	v_mul_f32_e32 v7, v16, v7
	v_mul_f32_e32 v8, v32, v8
	v_bfe_u32 v9, v6, 16, 1
	v_bfe_u32 v10, v7, 16, 1
	v_bfe_u32 v11, v8, 16, 1
	v_add3_u32 v6, v6, v9, s75
	v_mul_f32_e32 v1, v60, v1
	v_add3_u32 v7, v7, v10, s75
	ds_write_b16_d16_hi v234, v6 offset:43008
	ds_write_b16_d16_hi v234, v7 offset:43072
	v_add3_u32 v6, v8, v11, s75
	v_mul_f32_e32 v1, v48, v1
	ds_write_b16_d16_hi v234, v6 offset:43136
	v_bfe_u32 v6, v1, 16, 1
	v_add3_u32 v1, v1, v6, s75
	ds_write_b16_d16_hi v234, v1 offset:43200
	v_mul_f32_e32 v1, v29, v29
	v_fmac_f32_e32 v1, v13, v13
	v_fmac_f32_e32 v1, v45, v45
	v_fmac_f32_e32 v1, v61, v61
	ds_bpermute_b32 v2, v154, v1
	s_waitcnt lgkmcnt(0)
	v_add_f32_e32 v1, v1, v2
	ds_bpermute_b32 v2, v155, v1
	s_waitcnt lgkmcnt(0)
	v_add_f32_e32 v1, v1, v2
	ds_bpermute_b32 v2, v156, v1
	s_waitcnt lgkmcnt(0)
	v_add_f32_e32 v1, v1, v2
	ds_bpermute_b32 v2, v157, v1
	s_waitcnt lgkmcnt(0)
	v_add_f32_e32 v1, v1, v2
	ds_bpermute_b32 v2, v158, v1
	s_waitcnt lgkmcnt(0)
	v_add_f32_e32 v1, v1, v2
	v_fmamk_f32 v1, v1, 0x3c000000, v160
	v_mul_f32_e32 v2, 0x4f800000, v1
	v_cmp_gt_f32_e32 vcc, s74, v1
	s_nop 1
	v_cndmask_b32_e32 v1, v1, v2, vcc
	v_sqrt_f32_e32 v2, v1
	s_nop 0
	v_add_u32_e32 v3, -1, v2
	v_add_u32_e32 v6, 1, v2
	v_fma_f32 v7, -v3, v2, v1
	v_fma_f32 v8, -v6, v2, v1
	v_cmp_ge_f32_e64 s[4:5], 0, v7
	s_nop 1
	v_cndmask_b32_e64 v2, v2, v3, s[4:5]
	v_cmp_lt_f32_e64 s[4:5], 0, v8
	s_nop 1
	v_cndmask_b32_e64 v2, v2, v6, s[4:5]
	v_mul_f32_e32 v3, 0x37800000, v2
	v_cndmask_b32_e32 v2, v2, v3, vcc
	v_cmp_class_f32_e32 vcc, v1, v161
	s_nop 1
	v_cndmask_b32_e32 v1, v2, v1, vcc
	v_div_scale_f32 v2, s[4:5], v1, v1, 1.0
	v_rcp_f32_e32 v3, v2
	v_div_scale_f32 v6, vcc, 1.0, v1, 1.0
	v_fma_f32 v7, -v2, v3, 1.0
	v_fmac_f32_e32 v3, v7, v3
	v_mul_f32_e32 v7, v6, v3
	v_fma_f32 v8, -v2, v7, v6
	v_fmac_f32_e32 v7, v8, v3
	v_fma_f32 v2, -v2, v7, v6
	v_div_fmas_f32 v2, v2, v3, v7
	v_div_fixup_f32 v1, v2, v1, 1.0
	v_mul_f32_e32 v2, v13, v1
	v_mul_f32_e32 v3, v29, v1
	v_mul_f32_e32 v6, v45, v1
	v_mul_f32_e32 v1, v61, v1
	v_mul_f32_e32 v2, v0, v2
	v_mul_f32_e32 v3, v16, v3
	v_mul_f32_e32 v6, v32, v6
	v_mul_f32_e32 v1, v48, v1
	v_bfe_u32 v7, v2, 16, 1
	v_bfe_u32 v8, v3, 16, 1
	v_bfe_u32 v9, v6, 16, 1
	v_bfe_u32 v10, v1, 16, 1
	v_add3_u32 v2, v2, v7, s75
	v_add3_u32 v3, v3, v8, s75
	v_add3_u32 v6, v6, v9, s75
	v_add3_u32 v1, v1, v10, s75
	ds_write_b16_d16_hi v234, v2 offset:43264
	ds_write_b16_d16_hi v234, v3 offset:43328
	ds_write_b16_d16_hi v234, v6 offset:43392
	ds_write_b16_d16_hi v234, v1 offset:43456
	v_mul_f32_e32 v1, v30, v30
	v_fmac_f32_e32 v1, v14, v14
	v_fmac_f32_e32 v1, v46, v46
	v_fmac_f32_e32 v1, v62, v62
	ds_bpermute_b32 v2, v154, v1
	s_waitcnt lgkmcnt(0)
; #define SBAR() __builtin_amdgcn_sched_barrier(0)
; __device__ __forceinline__ int crow(int r, int hi) { return (r & 3) + 8 * (r >> 2) + 4 * hi; }
; __device__ __forceinline__ unsigned short f2bf(float f) { unsigned u = __float_as_uint(f); return (unsigned short)((u + 0x7fffu + ((u >> 16) & 1u)) >> 16); }
; __device__ __forceinline__ unsigned f2bf(float f) { unsigned u = __float_as_uint(f); return (u + 0x7fffu + ((u >> 16) & 1u)) >> 16; }
; #define AIN(i) ((const float*)ldarg(i))
; #define G lgrid()
; template <bool DIFF> ...
;     ...
;     for (int r = 0; r < 16; ++r) {
;       float ss = o[0][r] * o[0][r] + o[1][r] * o[1][r] + o[2][r] * o[2][r] + o[3][r] * o[3][r];
;       ss += __shfl_xor(ss, 1); ss += __shfl_xor(ss, 2); ss += __shfl_xor(ss, 4); ss += __shfl_xor(ss, 8); ss += __shfl_xor(ss, 16);
;       const float rs = 1.0f / sqrtf(ss * (1.0f / 128.0f) + 1e-6f);
;       bf16* orow = Ow + (size_t)crow(r, hi) * 2048 + r32;
; #pragma unroll
;       for (int d = 0; d < 4; ++d) orow[32 * d] = f2bf(o[d][r] * rs * gsub[d]);
;       asm volatile("" ::: "memory"); SBAR();
; __global__ void __launch_bounds__(NTHR, 2) mega_fwd(Args a_unused) {
;     ...
;     for (int u = vcu; u < 1536; u += G) {
;       int s, h, qb, L;
;       if (u < 1024) { qb = u & 15; const int bh = u >> 4; h = bh & 7; s = 8 + (bh >> 3); L = 4096; }
;       else { const int v = u - 1024; qb = v & 7; const int bh = v >> 3; h = bh & 7; s = bh >> 3; L = 2048; }
;       const size_t mbase = s < 8 ? (size_t)s * 2048 : (size_t)TP + (size_t)(s - 8) * 4096;
;       att::attn_unit<true>(QA + (mbase + 256 * qb) * 1024 + 128 * h, KA + mbase * 1024 + 128 * h, VA + mbase * 1024 + 128 * h,
;                            O + (mbase + 256 * qb) * 2048 + 128 * h, 0, L / 64, 256 * qb, 0, lam, AIN(4), h, AIN(12), (char*)lds);
;     }
	v_add_f32_e32 v1, v1, v2
	ds_bpermute_b32 v2, v155, v1
	s_waitcnt lgkmcnt(0)
	v_add_f32_e32 v1, v1, v2
	ds_bpermute_b32 v2, v156, v1
	s_waitcnt lgkmcnt(0)
	v_add_f32_e32 v1, v1, v2
	ds_bpermute_b32 v2, v157, v1
	s_waitcnt lgkmcnt(0)
	v_add_f32_e32 v1, v1, v2
	ds_bpermute_b32 v2, v158, v1
	s_waitcnt lgkmcnt(0)
	v_add_f32_e32 v1, v1, v2
	v_fmamk_f32 v1, v1, 0x3c000000, v160
	v_mul_f32_e32 v2, 0x4f800000, v1
	v_cmp_gt_f32_e32 vcc, s74, v1
	s_nop 1
	v_cndmask_b32_e32 v1, v1, v2, vcc
	v_sqrt_f32_e32 v4, v1
	v_add_co_u32_e64 v2, s[4:5], s86, v64
	v_add_u32_e32 v5, -1, v4
	s_nop 0
	v_addc_co_u32_e64 v3, s[4:5], 0, v65, s[4:5]
	v_add_u32_e32 v6, 1, v4
	v_fma_f32 v7, -v5, v4, v1
	v_fma_f32 v8, -v6, v4, v1
	v_cmp_ge_f32_e64 s[4:5], 0, v7
	s_nop 1
	v_cndmask_b32_e64 v4, v4, v5, s[4:5]
	v_cmp_lt_f32_e64 s[4:5], 0, v8
	s_nop 1
	v_cndmask_b32_e64 v4, v4, v6, s[4:5]
	v_mul_f32_e32 v5, 0x37800000, v4
	v_cndmask_b32_e32 v4, v4, v5, vcc
	v_cmp_class_f32_e32 vcc, v1, v161
	s_nop 1
	v_cndmask_b32_e32 v1, v4, v1, vcc
	v_div_scale_f32 v6, s[4:5], v1, v1, 1.0
	v_rcp_f32_e32 v7, v6
	v_add_co_u32_e32 v4, vcc, s87, v64
	v_fma_f32 v9, -v6, v7, 1.0
	s_nop 0
	v_addc_co_u32_e32 v5, vcc, 0, v65, vcc
	v_div_scale_f32 v8, vcc, 1.0, v1, 1.0
	v_fmac_f32_e32 v7, v9, v7
	v_mul_f32_e32 v9, v8, v7
	v_fma_f32 v10, -v6, v9, v8
	v_fmac_f32_e32 v9, v10, v7
	v_fma_f32 v6, -v6, v9, v8
	v_div_fmas_f32 v6, v6, v7, v9
	v_div_fixup_f32 v1, v6, v1, 1.0
	v_mul_f32_e32 v6, v14, v1
	v_mul_f32_e32 v7, v30, v1
	v_mul_f32_e32 v8, v46, v1
	v_mul_f32_e32 v6, v0, v6
	v_mul_f32_e32 v7, v16, v7
	v_mul_f32_e32 v8, v32, v8
	v_bfe_u32 v9, v6, 16, 1
	v_bfe_u32 v10, v7, 16, 1
	v_bfe_u32 v11, v8, 16, 1
	v_add3_u32 v6, v6, v9, s75
	v_mul_f32_e32 v1, v62, v1
	v_add3_u32 v7, v7, v10, s75
	ds_write_b16_d16_hi v234, v6 offset:43520
	ds_write_b16_d16_hi v234, v7 offset:43584
	v_add3_u32 v6, v8, v11, s75
	v_mul_f32_e32 v1, v48, v1
	ds_write_b16_d16_hi v234, v6 offset:43648
	v_bfe_u32 v6, v1, 16, 1
	v_add3_u32 v1, v1, v6, s75
	ds_write_b16_d16_hi v234, v1 offset:43712
	v_mul_f32_e32 v1, v31, v31
	v_fmac_f32_e32 v1, v15, v15
	v_fmac_f32_e32 v1, v47, v47
	v_fmac_f32_e32 v1, v63, v63
	ds_bpermute_b32 v2, v154, v1
	s_waitcnt lgkmcnt(0)
	v_add_f32_e32 v1, v1, v2
	ds_bpermute_b32 v2, v155, v1
	s_waitcnt lgkmcnt(0)
	v_add_f32_e32 v1, v1, v2
	ds_bpermute_b32 v2, v156, v1
	s_waitcnt lgkmcnt(0)
	v_add_f32_e32 v1, v1, v2
	ds_bpermute_b32 v2, v157, v1
	s_waitcnt lgkmcnt(0)
	v_add_f32_e32 v1, v1, v2
	ds_bpermute_b32 v2, v158, v1
	s_waitcnt lgkmcnt(0)
	v_add_f32_e32 v1, v1, v2
	v_fmamk_f32 v1, v1, 0x3c000000, v160
	v_mul_f32_e32 v2, 0x4f800000, v1
	v_cmp_gt_f32_e32 vcc, s74, v1
	s_nop 1
	v_cndmask_b32_e32 v1, v1, v2, vcc
	v_sqrt_f32_e32 v2, v1
	s_nop 0
	v_add_u32_e32 v3, -1, v2
	v_add_u32_e32 v6, 1, v2
	v_fma_f32 v7, -v3, v2, v1
	v_fma_f32 v8, -v6, v2, v1
	v_cmp_ge_f32_e64 s[4:5], 0, v7
	s_nop 1
	v_cndmask_b32_e64 v2, v2, v3, s[4:5]
	v_cmp_lt_f32_e64 s[4:5], 0, v8
	s_nop 1
	v_cndmask_b32_e64 v2, v2, v6, s[4:5]
	v_mul_f32_e32 v3, 0x37800000, v2
	v_cndmask_b32_e32 v2, v2, v3, vcc
	v_cmp_class_f32_e32 vcc, v1, v161
	s_nop 1
	v_cndmask_b32_e32 v1, v2, v1, vcc
	v_div_scale_f32 v2, s[4:5], v1, v1, 1.0
	v_rcp_f32_e32 v3, v2
	v_div_scale_f32 v6, vcc, 1.0, v1, 1.0
	v_fma_f32 v7, -v2, v3, 1.0
	v_fmac_f32_e32 v3, v7, v3
	v_mul_f32_e32 v7, v6, v3
	v_fma_f32 v8, -v2, v7, v6
	v_fmac_f32_e32 v7, v8, v3
	v_fma_f32 v2, -v2, v7, v6
	v_div_fmas_f32 v2, v2, v3, v7
	v_div_fixup_f32 v1, v2, v1, 1.0
	v_mul_f32_e32 v2, v15, v1
	v_mul_f32_e32 v3, v31, v1
	v_mul_f32_e32 v6, v47, v1
	v_mul_f32_e32 v1, v63, v1
	v_mul_f32_e32 v0, v0, v2
	v_mul_f32_e32 v2, v16, v3
	v_mul_f32_e32 v3, v32, v6
	v_mul_f32_e32 v1, v48, v1
	v_bfe_u32 v6, v0, 16, 1
	v_bfe_u32 v7, v2, 16, 1
	v_bfe_u32 v8, v3, 16, 1
	v_bfe_u32 v9, v1, 16, 1
	v_add3_u32 v0, v0, v6, s75
	v_add3_u32 v2, v2, v7, s75
	v_add3_u32 v3, v3, v8, s75
	v_add3_u32 v1, v1, v9, s75
	ds_write_b16_d16_hi v234, v0 offset:43776
	ds_write_b16_d16_hi v234, v2 offset:43840
	ds_write_b16_d16_hi v234, v3 offset:43904
	ds_write_b16_d16_hi v234, v1 offset:43968
	s_waitcnt lgkmcnt(0)
	v_lshrrev_b32_e32 v234, 6, v208
	v_lshlrev_b32_e32 v234, 13, v234
	v_and_b32_e32 v235, 63, v208
	v_lshl_add_u32 v234, v235, 4, v234
	ds_read_b128 v[92:95], v234 offset:36864
	ds_read_b128 v[96:99], v234 offset:37888
	ds_read_b128 v[100:103], v234 offset:38912
	ds_read_b128 v[104:107], v234 offset:39936
	ds_read_b128 v[108:111], v234 offset:40960
	ds_read_b128 v[112:115], v234 offset:41984
	ds_read_b128 v[116:119], v234 offset:43008
	ds_read_b128 v[120:123], v234 offset:44032
	v_bfe_u32 v234, v208, 4, 2
	v_lshlrev_b32_e32 v234, 12, v234
	v_and_b32_e32 v235, 15, v208
	v_lshl_add_u32 v234, v235, 4, v234
	v_bfe_u32 v235, v208, 5, 1
	v_lshlrev_b32_e32 v235, 14, v235
	v_sub_u32_e32 v234, v234, v235
	v_and_b32_e32 v235, 31, v208
	v_lshlrev_b32_e32 v235, 1, v235
	v_sub_u32_e32 v234, v234, v235
	v_ashrrev_i32_e32 v235, 31, v234
	v_lshl_add_u64 v[236:237], v[234:235], 0, v[236:237]
	s_mov_b64 s[38:39], 0x4000
	s_waitcnt lgkmcnt(7)
	global_store_dwordx4 v[236:237], v[92:95], off
	v_lshl_add_u64 v[236:237], v[236:237], 0, s[38:39]
	s_waitcnt lgkmcnt(6)
	global_store_dwordx4 v[236:237], v[96:99], off
	v_lshl_add_u64 v[236:237], v[236:237], 0, s[38:39]
	s_waitcnt lgkmcnt(5)
	global_store_dwordx4 v[236:237], v[100:103], off
	v_lshl_add_u64 v[236:237], v[236:237], 0, s[38:39]
	s_waitcnt lgkmcnt(4)
	global_store_dwordx4 v[236:237], v[104:107], off
	v_lshl_add_u64 v[236:237], v[236:237], 0, s[38:39]
	s_waitcnt lgkmcnt(3)
	global_store_dwordx4 v[236:237], v[108:111], off
	v_lshl_add_u64 v[236:237], v[236:237], 0, s[38:39]
	s_waitcnt lgkmcnt(2)
	global_store_dwordx4 v[236:237], v[112:115], off
	v_lshl_add_u64 v[236:237], v[236:237], 0, s[38:39]
	s_waitcnt lgkmcnt(1)
	global_store_dwordx4 v[236:237], v[116:119], off
	v_lshl_add_u64 v[236:237], v[236:237], 0, s[38:39]
	s_waitcnt lgkmcnt(0)
	global_store_dwordx4 v[236:237], v[120:123], off
	s_load_dwordx2 s[4:5], s[0:1], 0x100
	s_waitcnt lgkmcnt(0)
	s_mov_b32 s2, s4
	s_add_i32 s88, s2, s88
	s_cmpk_lt_i32 s88, 0x600
	s_cbranch_scc0 .LBB0_345

; #define SBAR() __builtin_amdgcn_sched_barrier(0)
; __device__ __forceinline__ int crow(int r, int hi) { return (r & 3) + 8 * (r >> 2) + 4 * hi; }
; __device__ __forceinline__ unsigned short f2bf(float f) { unsigned u = __float_as_uint(f); return (unsigned short)((u + 0x7fffu + ((u >> 16) & 1u)) >> 16); }
; __device__ __forceinline__ unsigned f2bf(float f) { unsigned u = __float_as_uint(f); return (u + 0x7fffu + ((u >> 16) & 1u)) >> 16; }
; template <bool DIFF> ...
;     ...
; #pragma unroll
;     for (int r = 0; r < 16; ++r) { bf16* orow = Ow + (size_t)crow(r, hi) * 2048 + r32; const float rl = 1.0f / wsc[32 + crow(r, hi)];
; #pragma unroll
;       for (int d = 0; d < 4; ++d) orow[32 * d] = f2bf(o[d][r] * rl);
;       asm volatile("" ::: "memory"); SBAR(); }
.LBB0_346:
	s_or_b64 exec, exec, s[4:5]
	s_waitcnt lgkmcnt(0)
	v_lshl_add_u32 v68, v154, 4, v156
	s_lshl_b64 s[4:5], s[52:53], 12
	ds_read_b32 v69, v68 offset:34944
	s_add_u32 s2, s42, s4
	s_addc_u32 s5, s43, s5
	s_lshl_b32 s4, s44, 1
	s_add_u32 s4, s2, s4
	v_ashrrev_i32_e32 v147, 31, v146
	s_addc_u32 s5, s5, 0
	v_lshlrev_b64 v[66:67], 12, v[146:147]
	v_lshl_add_u64 v[66:67], s[4:5], 0, v[66:67]
	s_waitcnt lgkmcnt(0)
	v_div_scale_f32 v72, s[4:5], v69, v69, 1.0
	v_rcp_f32_e32 v73, v72
	v_lshlrev_b32_e32 v0, 1, v155
	v_lshl_add_u64 v[66:67], v[66:67], 0, v[0:1]
	v_lshlrev_b32_e32 v0, 14, v154
	v_fma_f32 v74, -v72, v73, 1.0
	v_fmac_f32_e32 v73, v74, v73
	v_div_scale_f32 v74, vcc, 1.0, v69, 1.0
	v_mul_f32_e32 v75, v74, v73
	v_fma_f32 v76, -v72, v75, v74
	v_fmac_f32_e32 v75, v76, v73
	v_fma_f32 v72, -v72, v75, v74
	v_div_fmas_f32 v72, v72, v73, v75
	v_div_fixup_f32 v69, v72, v69, 1.0
	v_mul_f32_e32 v50, v50, v69
	v_bfe_u32 v72, v50, 16, 1
	v_lshl_add_u64 v[70:71], v[66:67], 0, v[0:1]
	v_add3_u32 v50, v50, v72, s97
	v_mul_f32_e32 v34, v34, v69
	v_lshrrev_b32_e32 v234, 6, v208
	v_lshlrev_b32_e32 v234, 13, v234
	v_bfe_u32 v235, v208, 5, 1
	v_lshl_add_u32 v234, v235, 10, v234
	v_and_b32_e32 v235, 31, v208
	v_lshl_add_u32 v234, v235, 1, v234
	v_mov_b32_e32 v236, v70
	v_mov_b32_e32 v237, v71
	ds_write_b16_d16_hi v234, v50 offset:36864
	v_bfe_u32 v50, v34, 16, 1
	v_add3_u32 v34, v34, v50, s97
	v_mul_f32_e32 v18, v18, v69
	ds_write_b16_d16_hi v234, v34 offset:36928
	v_bfe_u32 v34, v18, 16, 1
	v_add3_u32 v18, v18, v34, s97
	v_mul_f32_e32 v2, v2, v69
	ds_write_b16_d16_hi v234, v18 offset:36992
	v_bfe_u32 v18, v2, 16, 1
	v_add3_u32 v2, v2, v18, s97
	ds_write_b16_d16_hi v234, v2 offset:37056
	ds_read_b32 v2, v68 offset:34948
	v_or_b32_e32 v70, 0x1000, v0
	v_mov_b32_e32 v71, v1
	v_lshl_add_u64 v[70:71], v[66:67], 0, v[70:71]
	s_waitcnt lgkmcnt(0)
	v_div_scale_f32 v18, s[4:5], v2, v2, 1.0
	v_rcp_f32_e32 v34, v18
	v_div_scale_f32 v50, vcc, 1.0, v2, 1.0
	v_fma_f32 v69, -v18, v34, 1.0
	v_fmac_f32_e32 v34, v69, v34
	v_mul_f32_e32 v69, v50, v34
	v_fma_f32 v72, -v18, v69, v50
	v_fmac_f32_e32 v69, v72, v34
	v_fma_f32 v18, -v18, v69, v50
	v_div_fmas_f32 v18, v18, v34, v69
	v_div_fixup_f32 v2, v18, v2, 1.0
	v_mul_f32_e32 v18, v51, v2
	v_bfe_u32 v34, v18, 16, 1
	v_add3_u32 v18, v18, v34, s97
	ds_write_b16_d16_hi v234, v18 offset:37120
	v_mul_f32_e32 v18, v35, v2
	v_bfe_u32 v34, v18, 16, 1
	v_add3_u32 v18, v18, v34, s97
	ds_write_b16_d16_hi v234, v18 offset:37184
	v_mul_f32_e32 v18, v19, v2
	v_mul_f32_e32 v2, v3, v2
	v_bfe_u32 v19, v18, 16, 1
	v_bfe_u32 v3, v2, 16, 1
	v_add3_u32 v18, v18, v19, s97
	v_add3_u32 v2, v2, v3, s97
	ds_write_b16_d16_hi v234, v18 offset:37248
	ds_write_b16_d16_hi v234, v2 offset:37312
	ds_read_b32 v18, v68 offset:34952
	v_or_b32_e32 v2, 0x2000, v0
	v_mov_b32_e32 v3, v1
	v_lshl_add_u64 v[2:3], v[66:67], 0, v[2:3]
	s_waitcnt lgkmcnt(0)
	v_div_scale_f32 v19, s[4:5], v18, v18, 1.0
	v_rcp_f32_e32 v34, v19
	v_div_scale_f32 v35, vcc, 1.0, v18, 1.0
	v_fma_f32 v50, -v19, v34, 1.0
	v_fmac_f32_e32 v34, v50, v34
	v_mul_f32_e32 v50, v35, v34
	v_fma_f32 v51, -v19, v50, v35
	v_fmac_f32_e32 v50, v51, v34
	v_fma_f32 v19, -v19, v50, v35
	v_div_fmas_f32 v19, v19, v34, v50
	v_div_fixup_f32 v18, v19, v18, 1.0
	v_mul_f32_e32 v19, v52, v18
	v_bfe_u32 v34, v19, 16, 1
	v_add3_u32 v19, v19, v34, s97
	ds_write_b16_d16_hi v234, v19 offset:37376
	v_mul_f32_e32 v19, v36, v18
	v_bfe_u32 v34, v19, 16, 1
	v_add3_u32 v19, v19, v34, s97
	ds_write_b16_d16_hi v234, v19 offset:37440
	v_mul_f32_e32 v19, v20, v18
	v_mul_f32_e32 v4, v4, v18
	v_bfe_u32 v20, v19, 16, 1
	v_bfe_u32 v18, v4, 16, 1
	v_add3_u32 v19, v19, v20, s97
	v_add3_u32 v4, v4, v18, s97
	ds_write_b16_d16_hi v234, v19 offset:37504
	ds_write_b16_d16_hi v234, v4 offset:37568
	ds_read_b32 v4, v68 offset:34956
	v_or_b32_e32 v2, 0x3000, v0
	v_mov_b32_e32 v3, v1
	v_lshl_add_u64 v[2:3], v[66:67], 0, v[2:3]
	s_waitcnt lgkmcnt(0)
	v_div_scale_f32 v18, s[4:5], v4, v4, 1.0
	v_rcp_f32_e32 v19, v18
	v_div_scale_f32 v20, vcc, 1.0, v4, 1.0
	v_fma_f32 v34, -v18, v19, 1.0
	v_fmac_f32_e32 v19, v34, v19
	v_mul_f32_e32 v34, v20, v19
	v_fma_f32 v35, -v18, v34, v20
	v_fmac_f32_e32 v34, v35, v19
	v_fma_f32 v18, -v18, v34, v20
	v_div_fmas_f32 v18, v18, v19, v34
	v_div_fixup_f32 v4, v18, v4, 1.0
	v_mul_f32_e32 v18, v53, v4
	v_bfe_u32 v19, v18, 16, 1
	v_add3_u32 v18, v18, v19, s97
	ds_write_b16_d16_hi v234, v18 offset:37632
	v_mul_f32_e32 v18, v37, v4
	v_bfe_u32 v19, v18, 16, 1
	v_add3_u32 v18, v18, v19, s97
	ds_write_b16_d16_hi v234, v18 offset:37696
	v_mul_f32_e32 v18, v21, v4
	v_mul_f32_e32 v4, v5, v4
	v_bfe_u32 v19, v18, 16, 1
	v_bfe_u32 v5, v4, 16, 1
	v_add3_u32 v18, v18, v19, s97
	v_add3_u32 v4, v4, v5, s97
	ds_write_b16_d16_hi v234, v18 offset:37760
	ds_write_b16_d16_hi v234, v4 offset:37824
	ds_read_b32 v4, v68 offset:34976
	v_or_b32_e32 v2, 0x8000, v0
	v_mov_b32_e32 v3, v1
	v_lshl_add_u64 v[2:3], v[66:67], 0, v[2:3]
	s_waitcnt lgkmcnt(0)
	v_div_scale_f32 v5, s[4:5], v4, v4, 1.0
	v_rcp_f32_e32 v18, v5
	v_div_scale_f32 v19, vcc, 1.0, v4, 1.0
	v_fma_f32 v20, -v5, v18, 1.0
	v_fmac_f32_e32 v18, v20, v18
	v_mul_f32_e32 v20, v19, v18
	v_fma_f32 v21, -v5, v20, v19
	v_fmac_f32_e32 v20, v21, v18
	v_fma_f32 v5, -v5, v20, v19
	v_div_fmas_f32 v5, v5, v18, v20
	v_div_fixup_f32 v4, v5, v4, 1.0
	v_mul_f32_e32 v5, v54, v4
	v_bfe_u32 v18, v5, 16, 1
	v_add3_u32 v5, v5, v18, s97
	ds_write_b16_d16_hi v234, v5 offset:38912
	v_mul_f32_e32 v5, v38, v4
	v_bfe_u32 v18, v5, 16, 1
	v_add3_u32 v5, v5, v18, s97
	ds_write_b16_d16_hi v234, v5 offset:38976
	v_mul_f32_e32 v5, v22, v4
	v_bfe_u32 v18, v5, 16, 1
	v_add3_u32 v5, v5, v18, s97
	v_mul_f32_e32 v4, v6, v4
	ds_write_b16_d16_hi v234, v5 offset:39040
	v_bfe_u32 v5, v4, 16, 1
	v_add3_u32 v4, v4, v5, s97
	ds_write_b16_d16_hi v234, v4 offset:39104
	ds_read_b32 v4, v68 offset:34980
	v_or_b32_e32 v2, 0x9000, v0
	v_mov_b32_e32 v3, v1
	v_lshl_add_u64 v[2:3], v[66:67], 0, v[2:3]
	s_waitcnt lgkmcnt(0)
; #define SBAR() __builtin_amdgcn_sched_barrier(0)
; __device__ __forceinline__ int crow(int r, int hi) { return (r & 3) + 8 * (r >> 2) + 4 * hi; }
; __device__ __forceinline__ unsigned short f2bf(float f) { unsigned u = __float_as_uint(f); return (unsigned short)((u + 0x7fffu + ((u >> 16) & 1u)) >> 16); }
; __device__ __forceinline__ unsigned f2bf(float f) { unsigned u = __float_as_uint(f); return (u + 0x7fffu + ((u >> 16) & 1u)) >> 16; }
; template <bool DIFF> ...
;     ...
; #pragma unroll
;     for (int r = 0; r < 16; ++r) { bf16* orow = Ow + (size_t)crow(r, hi) * 2048 + r32; const float rl = 1.0f / wsc[32 + crow(r, hi)];
; #pragma unroll
;       for (int d = 0; d < 4; ++d) orow[32 * d] = f2bf(o[d][r] * rl);
;       asm volatile("" ::: "memory"); SBAR(); }
	v_div_scale_f32 v5, s[4:5], v4, v4, 1.0
	v_rcp_f32_e32 v6, v5
	v_div_scale_f32 v18, vcc, 1.0, v4, 1.0
	v_fma_f32 v19, -v5, v6, 1.0
	v_fmac_f32_e32 v6, v19, v6
	v_mul_f32_e32 v19, v18, v6
	v_fma_f32 v20, -v5, v19, v18
	v_fmac_f32_e32 v19, v20, v6
	v_fma_f32 v5, -v5, v19, v18
	v_div_fmas_f32 v5, v5, v6, v19
	v_div_fixup_f32 v4, v5, v4, 1.0
	v_mul_f32_e32 v5, v55, v4
	v_bfe_u32 v6, v5, 16, 1
	v_add3_u32 v5, v5, v6, s97
	ds_write_b16_d16_hi v234, v5 offset:39168
	v_mul_f32_e32 v5, v39, v4
	v_bfe_u32 v6, v5, 16, 1
	v_add3_u32 v5, v5, v6, s97
	ds_write_b16_d16_hi v234, v5 offset:39232
	v_mul_f32_e32 v5, v23, v4
	v_bfe_u32 v6, v5, 16, 1
	v_add3_u32 v5, v5, v6, s97
	v_mul_f32_e32 v4, v7, v4
	ds_write_b16_d16_hi v234, v5 offset:39296
	v_bfe_u32 v5, v4, 16, 1
	v_add3_u32 v4, v4, v5, s97
	ds_write_b16_d16_hi v234, v4 offset:39360
	ds_read_b32 v4, v68 offset:34984
	v_or_b32_e32 v2, 0xa000, v0
	v_mov_b32_e32 v3, v1
	v_lshl_add_u64 v[2:3], v[66:67], 0, v[2:3]
	s_waitcnt lgkmcnt(0)
	v_div_scale_f32 v5, s[4:5], v4, v4, 1.0
	v_rcp_f32_e32 v6, v5
	v_div_scale_f32 v7, vcc, 1.0, v4, 1.0
	v_fma_f32 v18, -v5, v6, 1.0
	v_fmac_f32_e32 v6, v18, v6
	v_mul_f32_e32 v18, v7, v6
	v_fma_f32 v19, -v5, v18, v7
	v_fmac_f32_e32 v18, v19, v6
	v_fma_f32 v5, -v5, v18, v7
	v_div_fmas_f32 v5, v5, v6, v18
	v_div_fixup_f32 v4, v5, v4, 1.0
	v_mul_f32_e32 v5, v56, v4
	v_bfe_u32 v6, v5, 16, 1
	v_add3_u32 v5, v5, v6, s97
	ds_write_b16_d16_hi v234, v5 offset:39424
	v_mul_f32_e32 v5, v40, v4
	v_bfe_u32 v6, v5, 16, 1
	v_add3_u32 v5, v5, v6, s97
	ds_write_b16_d16_hi v234, v5 offset:39488
	v_mul_f32_e32 v5, v24, v4
	v_bfe_u32 v6, v5, 16, 1
	v_add3_u32 v5, v5, v6, s97
	v_mul_f32_e32 v4, v8, v4
	ds_write_b16_d16_hi v234, v5 offset:39552
	v_bfe_u32 v5, v4, 16, 1
	v_add3_u32 v4, v4, v5, s97
	ds_write_b16_d16_hi v234, v4 offset:39616
	ds_read_b32 v4, v68 offset:34988
	v_or_b32_e32 v2, 0xb000, v0
	v_mov_b32_e32 v3, v1
	v_lshl_add_u64 v[2:3], v[66:67], 0, v[2:3]
	s_waitcnt lgkmcnt(0)
	v_div_scale_f32 v5, s[4:5], v4, v4, 1.0
	v_rcp_f32_e32 v6, v5
	v_div_scale_f32 v7, vcc, 1.0, v4, 1.0
	v_fma_f32 v8, -v5, v6, 1.0
	v_fmac_f32_e32 v6, v8, v6
	v_mul_f32_e32 v8, v7, v6
	v_fma_f32 v18, -v5, v8, v7
	v_fmac_f32_e32 v8, v18, v6
	v_fma_f32 v5, -v5, v8, v7
	v_div_fmas_f32 v5, v5, v6, v8
	v_div_fixup_f32 v4, v5, v4, 1.0
	v_mul_f32_e32 v5, v57, v4
	v_bfe_u32 v6, v5, 16, 1
	v_add3_u32 v5, v5, v6, s97
	ds_write_b16_d16_hi v234, v5 offset:39680
	v_mul_f32_e32 v5, v41, v4
	v_bfe_u32 v6, v5, 16, 1
	v_add3_u32 v5, v5, v6, s97
	ds_write_b16_d16_hi v234, v5 offset:39744
	v_mul_f32_e32 v5, v25, v4
	v_bfe_u32 v6, v5, 16, 1
	v_add3_u32 v5, v5, v6, s97
	v_mul_f32_e32 v4, v9, v4
	ds_write_b16_d16_hi v234, v5 offset:39808
	v_bfe_u32 v5, v4, 16, 1
	v_add3_u32 v4, v4, v5, s97
	ds_write_b16_d16_hi v234, v4 offset:39872
	ds_read_b32 v4, v68 offset:35008
	v_or_b32_e32 v2, 0x10000, v0
	v_mov_b32_e32 v3, v1
	v_lshl_add_u64 v[2:3], v[66:67], 0, v[2:3]
	s_waitcnt lgkmcnt(0)
	v_div_scale_f32 v5, s[4:5], v4, v4, 1.0
	v_rcp_f32_e32 v6, v5
	v_div_scale_f32 v7, vcc, 1.0, v4, 1.0
	v_fma_f32 v8, -v5, v6, 1.0
	v_fmac_f32_e32 v6, v8, v6
	v_mul_f32_e32 v8, v7, v6
	v_fma_f32 v9, -v5, v8, v7
	v_fmac_f32_e32 v8, v9, v6
	v_fma_f32 v5, -v5, v8, v7
	v_div_fmas_f32 v5, v5, v6, v8
	v_div_fixup_f32 v4, v5, v4, 1.0
	v_mul_f32_e32 v5, v58, v4
	v_bfe_u32 v6, v5, 16, 1
	v_add3_u32 v5, v5, v6, s97
	ds_write_b16_d16_hi v234, v5 offset:40960
	v_mul_f32_e32 v5, v42, v4
	v_bfe_u32 v6, v5, 16, 1
	v_add3_u32 v5, v5, v6, s97
	ds_write_b16_d16_hi v234, v5 offset:41024
	v_mul_f32_e32 v5, v26, v4
	v_bfe_u32 v6, v5, 16, 1
	v_add3_u32 v5, v5, v6, s97
	v_mul_f32_e32 v4, v10, v4
	ds_write_b16_d16_hi v234, v5 offset:41088
	v_bfe_u32 v5, v4, 16, 1
	v_add3_u32 v4, v4, v5, s97
	ds_write_b16_d16_hi v234, v4 offset:41152
	ds_read_b32 v4, v68 offset:35012
	v_or_b32_e32 v2, 0x11000, v0
	v_mov_b32_e32 v3, v1
	v_lshl_add_u64 v[2:3], v[66:67], 0, v[2:3]
	s_waitcnt lgkmcnt(0)
	v_div_scale_f32 v5, s[4:5], v4, v4, 1.0
	v_rcp_f32_e32 v6, v5
	v_div_scale_f32 v7, vcc, 1.0, v4, 1.0
	v_fma_f32 v8, -v5, v6, 1.0
	v_fmac_f32_e32 v6, v8, v6
	v_mul_f32_e32 v8, v7, v6
	v_fma_f32 v9, -v5, v8, v7
	v_fmac_f32_e32 v8, v9, v6
	v_fma_f32 v5, -v5, v8, v7
	v_div_fmas_f32 v5, v5, v6, v8
	v_div_fixup_f32 v4, v5, v4, 1.0
	v_mul_f32_e32 v5, v59, v4
	v_bfe_u32 v6, v5, 16, 1
	v_add3_u32 v5, v5, v6, s97
	ds_write_b16_d16_hi v234, v5 offset:41216
	v_mul_f32_e32 v5, v43, v4
	v_bfe_u32 v6, v5, 16, 1
	v_add3_u32 v5, v5, v6, s97
	ds_write_b16_d16_hi v234, v5 offset:41280
	v_mul_f32_e32 v5, v27, v4
	v_bfe_u32 v6, v5, 16, 1
	v_add3_u32 v5, v5, v6, s97
	v_mul_f32_e32 v4, v11, v4
	ds_write_b16_d16_hi v234, v5 offset:41344
	v_bfe_u32 v5, v4, 16, 1
	v_add3_u32 v4, v4, v5, s97
	ds_write_b16_d16_hi v234, v4 offset:41408
	ds_read_b32 v4, v68 offset:35016
	v_or_b32_e32 v2, 0x12000, v0
	v_mov_b32_e32 v3, v1
	v_lshl_add_u64 v[2:3], v[66:67], 0, v[2:3]
	s_waitcnt lgkmcnt(0)
	v_div_scale_f32 v5, s[4:5], v4, v4, 1.0
	v_rcp_f32_e32 v6, v5
	v_div_scale_f32 v7, vcc, 1.0, v4, 1.0
	v_fma_f32 v8, -v5, v6, 1.0
	v_fmac_f32_e32 v6, v8, v6
	v_mul_f32_e32 v8, v7, v6
	v_fma_f32 v9, -v5, v8, v7
	v_fmac_f32_e32 v8, v9, v6
	v_fma_f32 v5, -v5, v8, v7
	v_div_fmas_f32 v5, v5, v6, v8
	v_div_fixup_f32 v4, v5, v4, 1.0
	v_mul_f32_e32 v5, v60, v4
	v_bfe_u32 v6, v5, 16, 1
	v_add3_u32 v5, v5, v6, s97
	ds_write_b16_d16_hi v234, v5 offset:41472
	v_mul_f32_e32 v5, v44, v4
	v_bfe_u32 v6, v5, 16, 1
	v_add3_u32 v5, v5, v6, s97
	ds_write_b16_d16_hi v234, v5 offset:41536
	v_mul_f32_e32 v5, v28, v4
	v_bfe_u32 v6, v5, 16, 1
	v_add3_u32 v5, v5, v6, s97
	v_mul_f32_e32 v4, v12, v4
	ds_write_b16_d16_hi v234, v5 offset:41600
	v_bfe_u32 v5, v4, 16, 1
	v_add3_u32 v4, v4, v5, s97
	ds_write_b16_d16_hi v234, v4 offset:41664
	ds_read_b32 v4, v68 offset:35020
	v_or_b32_e32 v2, 0x13000, v0
	v_mov_b32_e32 v3, v1
	v_lshl_add_u64 v[2:3], v[66:67], 0, v[2:3]
	s_waitcnt lgkmcnt(0)
; #define SBAR() __builtin_amdgcn_sched_barrier(0)
; __device__ __forceinline__ int crow(int r, int hi) { return (r & 3) + 8 * (r >> 2) + 4 * hi; }
; __device__ __forceinline__ unsigned short f2bf(float f) { unsigned u = __float_as_uint(f); return (unsigned short)((u + 0x7fffu + ((u >> 16) & 1u)) >> 16); }
; __device__ __forceinline__ unsigned f2bf(float f) { unsigned u = __float_as_uint(f); return (u + 0x7fffu + ((u >> 16) & 1u)) >> 16; }
; #define AIN(i) ((const float*)ldarg(i))
; #define G lgrid()
; template <bool DIFF> ...
;     ...
; #pragma unroll
;     for (int r = 0; r < 16; ++r) { bf16* orow = Ow + (size_t)crow(r, hi) * 2048 + r32; const float rl = 1.0f / wsc[32 + crow(r, hi)];
; #pragma unroll
;       for (int d = 0; d < 4; ++d) orow[32 * d] = f2bf(o[d][r] * rl);
;       asm volatile("" ::: "memory"); SBAR(); }
; __global__ void __launch_bounds__(NTHR, 2) mega_fwd(Args a_unused) {
;     ...
;     for (int v = vcu; v < 1536; v += G) {
;       int s, h, rb, rows;
;       if (v < 1024) { rb = v & 15; const int bh = v >> 4; h = bh & 7; s = 8 + (bh >> 3); rows = 64; }
;       else { const int w = v - 1024; rb = w & 7; const int bh = w >> 3; h = bh & 7; s = bh >> 3; rows = 32; }
;       const size_t mbase = s < 8 ? (size_t)s * 2048 : (size_t)TP + (size_t)(s - 8) * 4096;
;       int tl = 4 * rb - 4; tl = tl < 0 ? 0 : (tl > rows - 8 ? rows - 8 : tl);
;       int th = 4 * rb + 3 - 4; th = th < 0 ? 0 : (th > rows - 8 ? rows - 8 : th); th += 8;
;       att::attn_unit<false>(QB + (mbase + 256 * rb) * 1024 + 128 * h, KB + mbase * 1024 + 128 * h, VB + mbase * 1024 + 128 * h,
;                             O + (mbase + 256 * rb) * 2048 + 1024 + 128 * h, tl, th, 4 * rb, rows, 0.f, AIN(13), h, nullptr, (char*)lds);
;     }
	v_div_scale_f32 v5, s[4:5], v4, v4, 1.0
	v_rcp_f32_e32 v6, v5
	v_div_scale_f32 v7, vcc, 1.0, v4, 1.0
	v_fma_f32 v8, -v5, v6, 1.0
	v_fmac_f32_e32 v6, v8, v6
	v_mul_f32_e32 v8, v7, v6
	v_fma_f32 v9, -v5, v8, v7
	v_fmac_f32_e32 v8, v9, v6
	v_fma_f32 v5, -v5, v8, v7
	v_div_fmas_f32 v5, v5, v6, v8
	v_div_fixup_f32 v4, v5, v4, 1.0
	v_mul_f32_e32 v5, v61, v4
	v_bfe_u32 v6, v5, 16, 1
	v_add3_u32 v5, v5, v6, s97
	ds_write_b16_d16_hi v234, v5 offset:41728
	v_mul_f32_e32 v5, v45, v4
	v_bfe_u32 v6, v5, 16, 1
	v_add3_u32 v5, v5, v6, s97
	ds_write_b16_d16_hi v234, v5 offset:41792
	v_mul_f32_e32 v5, v29, v4
	v_bfe_u32 v6, v5, 16, 1
	v_add3_u32 v5, v5, v6, s97
	v_mul_f32_e32 v4, v13, v4
	ds_write_b16_d16_hi v234, v5 offset:41856
	v_bfe_u32 v5, v4, 16, 1
	v_add3_u32 v4, v4, v5, s97
	ds_write_b16_d16_hi v234, v4 offset:41920
	ds_read_b32 v4, v68 offset:35040
	v_or_b32_e32 v2, 0x18000, v0
	v_mov_b32_e32 v3, v1
	v_lshl_add_u64 v[2:3], v[66:67], 0, v[2:3]
	s_waitcnt lgkmcnt(0)
	v_div_scale_f32 v5, s[4:5], v4, v4, 1.0
	v_rcp_f32_e32 v6, v5
	v_div_scale_f32 v7, vcc, 1.0, v4, 1.0
	v_fma_f32 v8, -v5, v6, 1.0
	v_fmac_f32_e32 v6, v8, v6
	v_mul_f32_e32 v8, v7, v6
	v_fma_f32 v9, -v5, v8, v7
	v_fmac_f32_e32 v8, v9, v6
	v_fma_f32 v5, -v5, v8, v7
	v_div_fmas_f32 v5, v5, v6, v8
	v_div_fixup_f32 v4, v5, v4, 1.0
	v_mul_f32_e32 v5, v62, v4
	v_bfe_u32 v6, v5, 16, 1
	v_add3_u32 v5, v5, v6, s97
	ds_write_b16_d16_hi v234, v5 offset:43008
	v_mul_f32_e32 v5, v46, v4
	v_bfe_u32 v6, v5, 16, 1
	v_add3_u32 v5, v5, v6, s97
	ds_write_b16_d16_hi v234, v5 offset:43072
	v_mul_f32_e32 v5, v30, v4
	v_bfe_u32 v6, v5, 16, 1
	v_add3_u32 v5, v5, v6, s97
	v_mul_f32_e32 v4, v14, v4
	ds_write_b16_d16_hi v234, v5 offset:43136
	v_bfe_u32 v5, v4, 16, 1
	v_add3_u32 v4, v4, v5, s97
	ds_write_b16_d16_hi v234, v4 offset:43200
	ds_read_b32 v4, v68 offset:35044
	v_or_b32_e32 v2, 0x19000, v0
	v_mov_b32_e32 v3, v1
	v_lshl_add_u64 v[2:3], v[66:67], 0, v[2:3]
	s_waitcnt lgkmcnt(0)
	v_div_scale_f32 v5, s[4:5], v4, v4, 1.0
	v_rcp_f32_e32 v6, v5
	v_div_scale_f32 v7, vcc, 1.0, v4, 1.0
	v_fma_f32 v8, -v5, v6, 1.0
	v_fmac_f32_e32 v6, v8, v6
	v_mul_f32_e32 v8, v7, v6
	v_fma_f32 v9, -v5, v8, v7
	v_fmac_f32_e32 v8, v9, v6
	v_fma_f32 v5, -v5, v8, v7
	v_div_fmas_f32 v5, v5, v6, v8
	v_div_fixup_f32 v4, v5, v4, 1.0
	v_mul_f32_e32 v5, v63, v4
	v_bfe_u32 v6, v5, 16, 1
	v_add3_u32 v5, v5, v6, s97
	ds_write_b16_d16_hi v234, v5 offset:43264
	v_mul_f32_e32 v5, v47, v4
	v_bfe_u32 v6, v5, 16, 1
	v_add3_u32 v5, v5, v6, s97
	ds_write_b16_d16_hi v234, v5 offset:43328
	v_mul_f32_e32 v5, v31, v4
	v_bfe_u32 v6, v5, 16, 1
	v_add3_u32 v5, v5, v6, s97
	v_mul_f32_e32 v4, v15, v4
	ds_write_b16_d16_hi v234, v5 offset:43392
	v_bfe_u32 v5, v4, 16, 1
	v_add3_u32 v4, v4, v5, s97
	ds_write_b16_d16_hi v234, v4 offset:43456
	ds_read_b32 v4, v68 offset:35048
	v_or_b32_e32 v2, 0x1a000, v0
	v_mov_b32_e32 v3, v1
	v_lshl_add_u64 v[2:3], v[66:67], 0, v[2:3]
	s_waitcnt lgkmcnt(0)
	v_div_scale_f32 v5, s[4:5], v4, v4, 1.0
	v_rcp_f32_e32 v6, v5
	v_div_scale_f32 v7, vcc, 1.0, v4, 1.0
	v_fma_f32 v8, -v5, v6, 1.0
	v_fmac_f32_e32 v6, v8, v6
	v_mul_f32_e32 v8, v7, v6
	v_fma_f32 v9, -v5, v8, v7
	v_fmac_f32_e32 v8, v9, v6
	v_fma_f32 v5, -v5, v8, v7
	v_div_fmas_f32 v5, v5, v6, v8
	v_div_fixup_f32 v4, v5, v4, 1.0
	v_mul_f32_e32 v5, v64, v4
	v_bfe_u32 v6, v5, 16, 1
	v_add3_u32 v5, v5, v6, s97
	ds_write_b16_d16_hi v234, v5 offset:43520
	v_mul_f32_e32 v5, v48, v4
	v_bfe_u32 v6, v5, 16, 1
	v_add3_u32 v5, v5, v6, s97
	ds_write_b16_d16_hi v234, v5 offset:43584
	v_mul_f32_e32 v5, v32, v4
	v_bfe_u32 v6, v5, 16, 1
	v_add3_u32 v5, v5, v6, s97
	v_mul_f32_e32 v4, v16, v4
	ds_write_b16_d16_hi v234, v5 offset:43648
	v_bfe_u32 v5, v4, 16, 1
	v_add3_u32 v4, v4, v5, s97
	ds_write_b16_d16_hi v234, v4 offset:43712
	ds_read_b32 v4, v68 offset:35052
	v_or_b32_e32 v0, 0x1b000, v0
	v_lshl_add_u64 v[2:3], v[66:67], 0, v[0:1]
	s_waitcnt lgkmcnt(0)
	v_div_scale_f32 v5, s[4:5], v4, v4, 1.0
	v_rcp_f32_e32 v6, v5
	v_div_scale_f32 v0, vcc, 1.0, v4, 1.0
	v_fma_f32 v7, -v5, v6, 1.0
	v_fmac_f32_e32 v6, v7, v6
	v_mul_f32_e32 v7, v0, v6
	v_fma_f32 v8, -v5, v7, v0
	v_fmac_f32_e32 v7, v8, v6
	v_fma_f32 v0, -v5, v7, v0
	v_div_fmas_f32 v0, v0, v6, v7
	v_div_fixup_f32 v0, v0, v4, 1.0
	v_mul_f32_e32 v4, v65, v0
	v_bfe_u32 v6, v4, 16, 1
	v_mul_f32_e32 v5, v49, v0
	v_add3_u32 v4, v4, v6, s97
	ds_write_b16_d16_hi v234, v4 offset:43776
	v_bfe_u32 v4, v5, 16, 1
	v_add3_u32 v4, v5, v4, s97
	ds_write_b16_d16_hi v234, v4 offset:43840
	v_mul_f32_e32 v4, v33, v0
	v_bfe_u32 v5, v4, 16, 1
	v_add3_u32 v4, v4, v5, s97
	v_mul_f32_e32 v0, v17, v0
	ds_write_b16_d16_hi v234, v4 offset:43904
	v_bfe_u32 v4, v0, 16, 1
	v_add3_u32 v0, v0, v4, s97
	ds_write_b16_d16_hi v234, v0 offset:43968
	s_waitcnt lgkmcnt(0)
	v_lshrrev_b32_e32 v234, 6, v208
	v_lshlrev_b32_e32 v234, 13, v234
	v_and_b32_e32 v235, 63, v208
	v_lshl_add_u32 v234, v235, 4, v234
	ds_read_b128 v[92:95], v234 offset:36864
	ds_read_b128 v[96:99], v234 offset:37888
	ds_read_b128 v[100:103], v234 offset:38912
	ds_read_b128 v[104:107], v234 offset:39936
	ds_read_b128 v[108:111], v234 offset:40960
	ds_read_b128 v[112:115], v234 offset:41984
	ds_read_b128 v[116:119], v234 offset:43008
	ds_read_b128 v[120:123], v234 offset:44032
	v_bfe_u32 v234, v208, 4, 2
	v_lshlrev_b32_e32 v234, 12, v234
	v_and_b32_e32 v235, 15, v208
	v_lshl_add_u32 v234, v235, 4, v234
	v_bfe_u32 v235, v208, 5, 1
	v_lshlrev_b32_e32 v235, 14, v235
	v_sub_u32_e32 v234, v234, v235
	v_and_b32_e32 v235, 31, v208
	v_lshlrev_b32_e32 v235, 1, v235
	v_sub_u32_e32 v234, v234, v235
	v_add_u32_e32 v234, 2048, v234
	v_ashrrev_i32_e32 v235, 31, v234
	v_lshl_add_u64 v[236:237], v[234:235], 0, v[236:237]
	s_mov_b64 s[38:39], 0x4000
	s_waitcnt lgkmcnt(7)
	global_store_dwordx4 v[236:237], v[92:95], off
	v_lshl_add_u64 v[236:237], v[236:237], 0, s[38:39]
	s_waitcnt lgkmcnt(6)
	global_store_dwordx4 v[236:237], v[96:99], off
	v_lshl_add_u64 v[236:237], v[236:237], 0, s[38:39]
	s_waitcnt lgkmcnt(5)
	global_store_dwordx4 v[236:237], v[100:103], off
	v_lshl_add_u64 v[236:237], v[236:237], 0, s[38:39]
	s_waitcnt lgkmcnt(4)
	global_store_dwordx4 v[236:237], v[104:107], off
	v_lshl_add_u64 v[236:237], v[236:237], 0, s[38:39]
	s_waitcnt lgkmcnt(3)
	global_store_dwordx4 v[236:237], v[108:111], off
	v_lshl_add_u64 v[236:237], v[236:237], 0, s[38:39]
	s_waitcnt lgkmcnt(2)
	global_store_dwordx4 v[236:237], v[112:115], off
	v_lshl_add_u64 v[236:237], v[236:237], 0, s[38:39]
	s_waitcnt lgkmcnt(1)
	global_store_dwordx4 v[236:237], v[116:119], off
	v_lshl_add_u64 v[236:237], v[236:237], 0, s[38:39]
	s_waitcnt lgkmcnt(0)
	global_store_dwordx4 v[236:237], v[120:123], off
	s_mov_b32 s2, s56
	s_add_i32 s33, s2, s33
	s_cmpk_gt_i32 s33, 0x5ff
	s_cbranch_scc1 .LBB0_448
